# v13 + GLU and DFT-stage-B GEMM epilogues: bias quads loaded once per unit and gelu-input segments fetched four at a time with counted waits instead of a load-wait round trip per accumulator quad
# baseline (speedup 1.0000x reference)
; __device__ __forceinline__ unsigned cvtpk(float lo, float hi) { unsigned r; asm volatile("v_cvt_pk_bf16_f32 %0, %1, %2" : "=v"(r) : "v"(lo), "v"(hi)); return r; }
; __device__ __forceinline__ float sigmoidf_(float x) { return __builtin_amdgcn_rcpf(1.f + __builtin_amdgcn_exp2f(x * -1.4426950408889634f)); }
;   __device__ __forceinline__ void operator()(const Acc& acc, const gm::Unit& u, int wr, int wc, int fr, int fq) const { const int pm = u.pm, pn = u.pn;
; #pragma unroll
;     for (int ai = 0; ai < 2; ++ai)
; #pragma unroll
;       for (int m = 0; m < 4; ++m) { const int row = pm * 256 + ai * 128 + wr * 64 + m * 16 + fr;
; #pragma unroll
;         for (int bj = 0; bj < 2; ++bj)
; #pragma unroll
;           for (int n = 0; n < 2; ++n) { const int col = pn * 256 + bj * 128 + wc * 32 + n * 16 + fq * 4; const f32x4 z = acc[ai][bj][m][n] + *(const f32x4*)(bg + col);
;             const u32x2 gw = *(const u32x2*)(Gg + (size_t)row * 512 + col);
;             const float g0 = __uint_as_float(gw[0] << 16), g1 = __uint_as_float(gw[0] & 0xffff0000u), g2 = __uint_as_float(gw[1] << 16), g3 = __uint_as_float(gw[1] & 0xffff0000u);
;             u32x2 w = {cvtpk(g0 * sigmoidf_(z[0]), g1 * sigmoidf_(z[1])), cvtpk(g2 * sigmoidf_(z[2]), g3 * sigmoidf_(z[3]))};
;             *(u32x2*)(Cat + (size_t)row * DM + 1024 + col) = w; } }
.LBB0_794:
	s_lshl_b32 s0, s0, 8
	v_mov_b32_e32 v138, v144
	v_mov_b32_e32 v139, v1
	s_or_b32 s0, s0, s87
	s_lshl_b32 s1, s68, 8
	v_lshl_add_u32 v142, v138, 2, s0
	s_add_i32 s1, s1, s86
	v_ashrrev_i32_e32 v143, 31, v142
	v_add_u32_e32 v140, s1, v139
	v_lshl_add_u64 v[138:139], v[142:143], 2, s[54:55]
	global_load_dwordx4 v[156:159], v[138:139], off
	global_load_dwordx4 v[160:163], v[138:139], off offset:64
	global_load_dwordx4 v[164:167], v[138:139], off offset:512
	global_load_dwordx4 v[168:171], v[138:139], off offset:576
	s_waitcnt vmcnt(3)
	v_mov_b64_e32 v[148:149], v[156:157]
	v_mov_b64_e32 v[150:151], v[158:159]
	v_ashrrev_i32_e32 v141, 31, v140
	v_lshlrev_b64 v[152:153], 10, v[140:141]
	v_lshlrev_b64 v[154:155], 12, v[140:141]
	s_mov_b64 s[68:69], -1
	s_andn2_b64 vcc, exec, s[66:67]
	v_pk_add_f32 v[150:151], v[128:129], v[150:151]
	v_pk_add_f32 v[148:149], v[126:127], v[148:149]
	v_lshl_add_u64 v[128:129], s[8:9], 0, v[152:153]
	v_lshlrev_b64 v[126:127], 1, v[142:143]
	v_lshl_add_u64 v[128:129], v[128:129], 0, v[126:127]
	global_load_dwordx2 v[172:173], v[128:129], off
	global_load_dwordx2 v[174:175], v[128:129], off offset:32
	global_load_dwordx2 v[176:177], v[128:129], off offset:256
	global_load_dwordx2 v[178:179], v[128:129], off offset:288
	s_waitcnt vmcnt(3)
	v_mov_b64_e32 v[142:143], v[172:173]
	v_mul_f32_e32 v148, 0xbfb8aa3b, v148
	v_exp_f32_e32 v148, v148
	v_lshlrev_b32_e32 v141, 16, v142
	v_add_f32_e32 v148, 1.0, v148
	v_rcp_f32_e32 v148, v148
	v_and_b32_e32 v142, 0xffff0000, v142
	v_lshlrev_b32_e32 v147, 16, v143
	v_and_b32_e32 v143, 0xffff0000, v143
	v_mul_f32_e32 v141, v148, v141
	v_mul_f32_e32 v148, 0xbfb8aa3b, v149
	v_exp_f32_e32 v148, v148
	s_nop 0
	v_add_f32_e32 v148, 1.0, v148
	v_rcp_f32_e32 v148, v148
	s_nop 0
	v_mul_f32_e32 v142, v148, v142
	v_cvt_pk_bf16_f32 v148, v141, v142
	v_mul_f32_e32 v142, 0xbfb8aa3b, v151
	v_mul_f32_e32 v141, 0xbfb8aa3b, v150
	v_exp_f32_e32 v142, v142
	v_exp_f32_e32 v141, v141
	v_add_f32_e32 v142, 1.0, v142
	v_add_f32_e32 v141, 1.0, v141
	v_rcp_f32_e32 v142, v142
	v_rcp_f32_e32 v141, v141
	v_mul_f32_e32 v142, v142, v143
	v_mul_f32_e32 v141, v141, v147
	v_cvt_pk_bf16_f32 v149, v141, v142
	v_lshl_add_u64 v[142:143], s[12:13], 0, v[154:155]
	v_lshl_add_u64 v[142:143], v[142:143], 0, v[126:127]
	global_store_dwordx2 v[142:143], v[148:149], off offset:2048
	s_waitcnt vmcnt(7)
	v_mov_b64_e32 v[148:149], v[160:161]
	v_mov_b64_e32 v[150:151], v[162:163]
	v_pk_add_f32 v[122:123], v[122:123], v[148:149]
	s_waitcnt vmcnt(3)
	v_mov_b64_e32 v[148:149], v[174:175]
	v_mul_f32_e32 v122, 0xbfb8aa3b, v122
	v_mul_f32_e32 v123, 0xbfb8aa3b, v123
	v_exp_f32_e32 v122, v122
	v_exp_f32_e32 v123, v123
	v_pk_add_f32 v[124:125], v[124:125], v[150:151]
	v_add_f32_e32 v122, 1.0, v122
	v_add_f32_e32 v123, 1.0, v123
	v_rcp_f32_e32 v122, v122
	v_rcp_f32_e32 v123, v123
	v_lshlrev_b32_e32 v141, 16, v148
	v_and_b32_e32 v147, 0xffff0000, v148
	v_mul_f32_e32 v122, v122, v141
	v_mul_f32_e32 v123, v123, v147
	v_cvt_pk_bf16_f32 v122, v122, v123
	v_mul_f32_e32 v123, 0xbfb8aa3b, v124
	v_exp_f32_e32 v123, v123
	v_mul_f32_e32 v124, 0xbfb8aa3b, v125
	v_exp_f32_e32 v124, v124
	v_lshlrev_b32_e32 v148, 16, v149
	v_add_f32_e32 v123, 1.0, v123
	v_rcp_f32_e32 v123, v123
	v_add_f32_e32 v124, 1.0, v124
	v_rcp_f32_e32 v124, v124
	v_and_b32_e32 v149, 0xffff0000, v149
	v_mul_f32_e32 v123, v123, v148
	v_mul_f32_e32 v124, v124, v149
	v_cvt_pk_bf16_f32 v123, v123, v124
	global_store_dwordx2 v[142:143], v[122:123], off offset:2080
	s_waitcnt vmcnt(7)
	v_mov_b64_e32 v[122:123], v[164:165]
	v_mov_b64_e32 v[124:125], v[166:167]
	v_pk_add_f32 v[118:119], v[118:119], v[122:123]
	s_waitcnt vmcnt(3)
	v_mov_b64_e32 v[122:123], v[176:177]
	v_mul_f32_e32 v118, 0xbfb8aa3b, v118
	v_mul_f32_e32 v119, 0xbfb8aa3b, v119
	v_exp_f32_e32 v118, v118
	v_exp_f32_e32 v119, v119
	v_pk_add_f32 v[120:121], v[120:121], v[124:125]
	v_add_f32_e32 v118, 1.0, v118
	v_add_f32_e32 v119, 1.0, v119
	v_rcp_f32_e32 v118, v118
	v_rcp_f32_e32 v119, v119
	v_lshlrev_b32_e32 v124, 16, v122
	v_and_b32_e32 v122, 0xffff0000, v122
	v_mul_f32_e32 v118, v118, v124
	v_mul_f32_e32 v119, v119, v122
	v_cvt_pk_bf16_f32 v118, v118, v119
	v_mul_f32_e32 v119, 0xbfb8aa3b, v120
	v_exp_f32_e32 v119, v119
	v_mul_f32_e32 v120, 0xbfb8aa3b, v121
	v_exp_f32_e32 v120, v120
	v_lshlrev_b32_e32 v125, 16, v123
	v_add_f32_e32 v119, 1.0, v119
	v_rcp_f32_e32 v119, v119
	v_add_f32_e32 v120, 1.0, v120
	v_rcp_f32_e32 v120, v120
	v_and_b32_e32 v123, 0xffff0000, v123
	v_mul_f32_e32 v119, v119, v125
	v_mul_f32_e32 v120, v120, v123
	v_cvt_pk_bf16_f32 v119, v119, v120
	global_store_dwordx2 v[142:143], v[118:119], off offset:2304
	s_waitcnt vmcnt(7)
	v_mov_b64_e32 v[118:119], v[168:169]
	v_mov_b64_e32 v[120:121], v[170:171]
	v_pk_add_f32 v[114:115], v[114:115], v[118:119]
	s_waitcnt vmcnt(3)
	v_mov_b64_e32 v[118:119], v[178:179]
	v_mul_f32_e32 v114, 0xbfb8aa3b, v114
	v_mul_f32_e32 v115, 0xbfb8aa3b, v115
	v_exp_f32_e32 v114, v114
	v_exp_f32_e32 v115, v115
	v_pk_add_f32 v[116:117], v[116:117], v[120:121]
	v_add_f32_e32 v114, 1.0, v114
	v_add_f32_e32 v115, 1.0, v115
	v_rcp_f32_e32 v114, v114
	v_rcp_f32_e32 v115, v115
	v_lshlrev_b32_e32 v120, 16, v118
	v_and_b32_e32 v118, 0xffff0000, v118
	v_mul_f32_e32 v114, v114, v120
	v_mul_f32_e32 v115, v115, v118
	v_cvt_pk_bf16_f32 v114, v114, v115
	v_mul_f32_e32 v115, 0xbfb8aa3b, v116
	v_exp_f32_e32 v115, v115
	v_mul_f32_e32 v116, 0xbfb8aa3b, v117
	v_exp_f32_e32 v116, v116
	v_lshlrev_b32_e32 v121, 16, v119
	v_add_f32_e32 v115, 1.0, v115
	v_rcp_f32_e32 v115, v115
	v_add_f32_e32 v116, 1.0, v116
	v_rcp_f32_e32 v116, v116
	v_and_b32_e32 v119, 0xffff0000, v119
	v_mul_f32_e32 v115, v115, v121
	v_mul_f32_e32 v116, v116, v119
	v_cvt_pk_bf16_f32 v115, v115, v116
	global_store_dwordx2 v[142:143], v[114:115], off offset:2336
	s_waitcnt vmcnt(11)
; __device__ __forceinline__ unsigned cvtpk(float lo, float hi) { unsigned r; asm volatile("v_cvt_pk_bf16_f32 %0, %1, %2" : "=v"(r) : "v"(lo), "v"(hi)); return r; }
; __device__ __forceinline__ float sigmoidf_(float x) { return __builtin_amdgcn_rcpf(1.f + __builtin_amdgcn_exp2f(x * -1.4426950408889634f)); }
;   __device__ __forceinline__ void operator()(const Acc& acc, const gm::Unit& u, int wr, int wc, int fr, int fq) const { const int pm = u.pm, pn = u.pn;
;     ...
;       for (int m = 0; m < 4; ++m) { const int row = pm * 256 + ai * 128 + wr * 64 + m * 16 + fr;
; #pragma unroll
;         for (int bj = 0; bj < 2; ++bj)
; #pragma unroll
;           for (int n = 0; n < 2; ++n) { const int col = pn * 256 + bj * 128 + wc * 32 + n * 16 + fq * 4; const f32x4 z = acc[ai][bj][m][n] + *(const f32x4*)(bg + col);
;             const u32x2 gw = *(const u32x2*)(Gg + (size_t)row * 512 + col);
;             const float g0 = __uint_as_float(gw[0] << 16), g1 = __uint_as_float(gw[0] & 0xffff0000u), g2 = __uint_as_float(gw[1] << 16), g3 = __uint_as_float(gw[1] & 0xffff0000u);
;             u32x2 w = {cvtpk(g0 * sigmoidf_(z[0]), g1 * sigmoidf_(z[1])), cvtpk(g2 * sigmoidf_(z[2]), g3 * sigmoidf_(z[3]))};
;             *(u32x2*)(Cat + (size_t)row * DM + 1024 + col) = w; } }
	v_mov_b64_e32 v[116:117], v[156:157]
	v_mov_b64_e32 v[118:119], v[158:159]
	v_add_u32_e32 v114, 16, v140
	v_ashrrev_i32_e32 v115, 31, v114
	v_lshlrev_b64 v[120:121], 10, v[114:115]
	v_lshlrev_b64 v[114:115], 12, v[114:115]
	v_pk_add_f32 v[116:117], v[110:111], v[116:117]
	v_lshl_add_u64 v[110:111], s[8:9], 0, v[120:121]
	v_lshl_add_u64 v[110:111], v[110:111], 0, v[126:127]
	v_pk_add_f32 v[112:113], v[112:113], v[118:119]
	global_load_dwordx2 v[180:181], v[110:111], off
	global_load_dwordx2 v[182:183], v[110:111], off offset:32
	global_load_dwordx2 v[184:185], v[110:111], off offset:256
	global_load_dwordx2 v[186:187], v[110:111], off offset:288
	s_waitcnt vmcnt(3)
	v_mov_b64_e32 v[118:119], v[180:181]
	v_mul_f32_e32 v116, 0xbfb8aa3b, v116
	v_mul_f32_e32 v117, 0xbfb8aa3b, v117
	v_mul_f32_e32 v112, 0xbfb8aa3b, v112
	v_mul_f32_e32 v113, 0xbfb8aa3b, v113
	v_exp_f32_e32 v116, v116
	v_exp_f32_e32 v117, v117
	v_exp_f32_e32 v112, v112
	v_exp_f32_e32 v113, v113
	v_add_f32_e32 v116, 1.0, v116
	v_add_f32_e32 v117, 1.0, v117
	v_add_f32_e32 v112, 1.0, v112
	v_add_f32_e32 v113, 1.0, v113
	v_rcp_f32_e32 v116, v116
	v_rcp_f32_e32 v117, v117
	v_rcp_f32_e32 v112, v112
	v_rcp_f32_e32 v113, v113
	v_lshlrev_b32_e32 v120, 16, v118
	v_and_b32_e32 v118, 0xffff0000, v118
	v_lshlrev_b32_e32 v121, 16, v119
	v_and_b32_e32 v119, 0xffff0000, v119
	v_mul_f32_e32 v116, v116, v120
	v_mul_f32_e32 v117, v117, v118
	v_mul_f32_e32 v112, v112, v121
	v_mul_f32_e32 v113, v113, v119
	v_cvt_pk_bf16_f32 v116, v116, v117
	v_cvt_pk_bf16_f32 v117, v112, v113
	v_lshl_add_u64 v[112:113], s[12:13], 0, v[114:115]
	v_lshl_add_u64 v[112:113], v[112:113], 0, v[126:127]
	global_store_dwordx2 v[112:113], v[116:117], off offset:2048
	s_waitcnt vmcnt(15)
	v_mov_b64_e32 v[114:115], v[160:161]
	v_mov_b64_e32 v[116:117], v[162:163]
	v_pk_add_f32 v[106:107], v[106:107], v[114:115]
	s_waitcnt vmcnt(3)
	v_mov_b64_e32 v[114:115], v[182:183]
	v_mul_f32_e32 v106, 0xbfb8aa3b, v106
	v_mul_f32_e32 v107, 0xbfb8aa3b, v107
	v_exp_f32_e32 v106, v106
	v_exp_f32_e32 v107, v107
	v_pk_add_f32 v[108:109], v[108:109], v[116:117]
	v_add_f32_e32 v106, 1.0, v106
	v_add_f32_e32 v107, 1.0, v107
	v_rcp_f32_e32 v106, v106
	v_rcp_f32_e32 v107, v107
	v_lshlrev_b32_e32 v116, 16, v114
	v_and_b32_e32 v114, 0xffff0000, v114
	v_mul_f32_e32 v106, v106, v116
	v_mul_f32_e32 v107, v107, v114
	v_cvt_pk_bf16_f32 v106, v106, v107
	v_mul_f32_e32 v107, 0xbfb8aa3b, v108
	v_exp_f32_e32 v107, v107
	v_mul_f32_e32 v108, 0xbfb8aa3b, v109
	v_exp_f32_e32 v108, v108
	v_lshlrev_b32_e32 v117, 16, v115
	v_add_f32_e32 v107, 1.0, v107
	v_rcp_f32_e32 v107, v107
	v_add_f32_e32 v108, 1.0, v108
	v_rcp_f32_e32 v108, v108
	v_and_b32_e32 v115, 0xffff0000, v115
	v_mul_f32_e32 v107, v107, v117
	v_mul_f32_e32 v108, v108, v115
	v_cvt_pk_bf16_f32 v107, v107, v108
	global_store_dwordx2 v[112:113], v[106:107], off offset:2080
	s_waitcnt vmcnt(15)
	v_mov_b64_e32 v[106:107], v[164:165]
	v_mov_b64_e32 v[108:109], v[166:167]
	v_pk_add_f32 v[102:103], v[102:103], v[106:107]
	s_waitcnt vmcnt(3)
	v_mov_b64_e32 v[106:107], v[184:185]
	v_mul_f32_e32 v102, 0xbfb8aa3b, v102
	v_mul_f32_e32 v103, 0xbfb8aa3b, v103
	v_exp_f32_e32 v102, v102
	v_exp_f32_e32 v103, v103
	v_pk_add_f32 v[104:105], v[104:105], v[108:109]
	v_add_f32_e32 v102, 1.0, v102
	v_add_f32_e32 v103, 1.0, v103
	v_rcp_f32_e32 v102, v102
	v_rcp_f32_e32 v103, v103
	v_lshlrev_b32_e32 v108, 16, v106
	v_and_b32_e32 v106, 0xffff0000, v106
	v_mul_f32_e32 v102, v102, v108
	v_mul_f32_e32 v103, v103, v106
	v_cvt_pk_bf16_f32 v102, v102, v103
	v_mul_f32_e32 v103, 0xbfb8aa3b, v104
	v_exp_f32_e32 v103, v103
	v_mul_f32_e32 v104, 0xbfb8aa3b, v105
	v_exp_f32_e32 v104, v104
	v_lshlrev_b32_e32 v109, 16, v107
	v_add_f32_e32 v103, 1.0, v103
	v_rcp_f32_e32 v103, v103
	v_add_f32_e32 v104, 1.0, v104
	v_rcp_f32_e32 v104, v104
	v_and_b32_e32 v107, 0xffff0000, v107
	v_mul_f32_e32 v103, v103, v109
	v_mul_f32_e32 v104, v104, v107
	v_cvt_pk_bf16_f32 v103, v103, v104
	global_store_dwordx2 v[112:113], v[102:103], off offset:2304
	s_waitcnt vmcnt(15)
	v_mov_b64_e32 v[102:103], v[168:169]
	v_mov_b64_e32 v[104:105], v[170:171]
	v_pk_add_f32 v[98:99], v[98:99], v[102:103]
	s_waitcnt vmcnt(3)
	v_mov_b64_e32 v[102:103], v[186:187]
	v_mul_f32_e32 v98, 0xbfb8aa3b, v98
	v_mul_f32_e32 v99, 0xbfb8aa3b, v99
	v_exp_f32_e32 v98, v98
	v_exp_f32_e32 v99, v99
	v_pk_add_f32 v[100:101], v[100:101], v[104:105]
	v_add_f32_e32 v98, 1.0, v98
	v_add_f32_e32 v99, 1.0, v99
	v_rcp_f32_e32 v98, v98
	v_rcp_f32_e32 v99, v99
	v_lshlrev_b32_e32 v104, 16, v102
	v_and_b32_e32 v102, 0xffff0000, v102
	v_mul_f32_e32 v98, v98, v104
	v_mul_f32_e32 v99, v99, v102
	v_cvt_pk_bf16_f32 v98, v98, v99
	v_mul_f32_e32 v99, 0xbfb8aa3b, v100
	v_exp_f32_e32 v99, v99
	v_mul_f32_e32 v100, 0xbfb8aa3b, v101
	v_exp_f32_e32 v100, v100
	v_lshlrev_b32_e32 v105, 16, v103
	v_add_f32_e32 v99, 1.0, v99
	v_rcp_f32_e32 v99, v99
	v_add_f32_e32 v100, 1.0, v100
	v_rcp_f32_e32 v100, v100
	v_and_b32_e32 v103, 0xffff0000, v103
	v_mul_f32_e32 v99, v99, v105
	v_mul_f32_e32 v100, v100, v103
	v_cvt_pk_bf16_f32 v99, v99, v100
	global_store_dwordx2 v[112:113], v[98:99], off offset:2336
	s_waitcnt vmcnt(19)
	v_mov_b64_e32 v[100:101], v[156:157]
	v_mov_b64_e32 v[102:103], v[158:159]
	v_add_u32_e32 v98, 32, v140
	v_ashrrev_i32_e32 v99, 31, v98
	v_lshlrev_b64 v[104:105], 10, v[98:99]
	v_lshlrev_b64 v[98:99], 12, v[98:99]
	v_pk_add_f32 v[100:101], v[94:95], v[100:101]
	v_lshl_add_u64 v[94:95], s[8:9], 0, v[104:105]
	v_lshl_add_u64 v[94:95], v[94:95], 0, v[126:127]
	v_pk_add_f32 v[96:97], v[96:97], v[102:103]
	global_load_dwordx2 v[172:173], v[94:95], off
	global_load_dwordx2 v[174:175], v[94:95], off offset:32
	global_load_dwordx2 v[176:177], v[94:95], off offset:256
	global_load_dwordx2 v[178:179], v[94:95], off offset:288
	s_waitcnt vmcnt(3)
; __device__ __forceinline__ unsigned cvtpk(float lo, float hi) { unsigned r; asm volatile("v_cvt_pk_bf16_f32 %0, %1, %2" : "=v"(r) : "v"(lo), "v"(hi)); return r; }
; __device__ __forceinline__ float sigmoidf_(float x) { return __builtin_amdgcn_rcpf(1.f + __builtin_amdgcn_exp2f(x * -1.4426950408889634f)); }
;   __device__ __forceinline__ void operator()(const Acc& acc, const gm::Unit& u, int wr, int wc, int fr, int fq) const { const int pm = u.pm, pn = u.pn;
;     ...
;       for (int m = 0; m < 4; ++m) { const int row = pm * 256 + ai * 128 + wr * 64 + m * 16 + fr;
; #pragma unroll
;         for (int bj = 0; bj < 2; ++bj)
; #pragma unroll
;           for (int n = 0; n < 2; ++n) { const int col = pn * 256 + bj * 128 + wc * 32 + n * 16 + fq * 4; const f32x4 z = acc[ai][bj][m][n] + *(const f32x4*)(bg + col);
;             const u32x2 gw = *(const u32x2*)(Gg + (size_t)row * 512 + col);
;             const float g0 = __uint_as_float(gw[0] << 16), g1 = __uint_as_float(gw[0] & 0xffff0000u), g2 = __uint_as_float(gw[1] << 16), g3 = __uint_as_float(gw[1] & 0xffff0000u);
;             u32x2 w = {cvtpk(g0 * sigmoidf_(z[0]), g1 * sigmoidf_(z[1])), cvtpk(g2 * sigmoidf_(z[2]), g3 * sigmoidf_(z[3]))};
;             *(u32x2*)(Cat + (size_t)row * DM + 1024 + col) = w; } }
	v_mov_b64_e32 v[102:103], v[172:173]
	v_mul_f32_e32 v100, 0xbfb8aa3b, v100
	v_mul_f32_e32 v101, 0xbfb8aa3b, v101
	v_mul_f32_e32 v96, 0xbfb8aa3b, v96
	v_mul_f32_e32 v97, 0xbfb8aa3b, v97
	v_exp_f32_e32 v100, v100
	v_exp_f32_e32 v101, v101
	v_exp_f32_e32 v96, v96
	v_exp_f32_e32 v97, v97
	v_add_f32_e32 v100, 1.0, v100
	v_add_f32_e32 v101, 1.0, v101
	v_add_f32_e32 v96, 1.0, v96
	v_add_f32_e32 v97, 1.0, v97
	v_rcp_f32_e32 v100, v100
	v_rcp_f32_e32 v101, v101
	v_rcp_f32_e32 v96, v96
	v_rcp_f32_e32 v97, v97
	v_lshlrev_b32_e32 v104, 16, v102
	v_and_b32_e32 v102, 0xffff0000, v102
	v_lshlrev_b32_e32 v105, 16, v103
	v_and_b32_e32 v103, 0xffff0000, v103
	v_mul_f32_e32 v100, v100, v104
	v_mul_f32_e32 v101, v101, v102
	v_mul_f32_e32 v96, v96, v105
	v_mul_f32_e32 v97, v97, v103
	v_cvt_pk_bf16_f32 v100, v100, v101
	v_cvt_pk_bf16_f32 v101, v96, v97
	v_lshl_add_u64 v[96:97], s[12:13], 0, v[98:99]
	v_lshl_add_u64 v[96:97], v[96:97], 0, v[126:127]
	global_store_dwordx2 v[96:97], v[100:101], off offset:2048
	s_waitcnt vmcnt(23)
	v_mov_b64_e32 v[98:99], v[160:161]
	v_mov_b64_e32 v[100:101], v[162:163]
	v_pk_add_f32 v[90:91], v[90:91], v[98:99]
	s_waitcnt vmcnt(3)
	v_mov_b64_e32 v[98:99], v[174:175]
	v_mul_f32_e32 v90, 0xbfb8aa3b, v90
	v_mul_f32_e32 v91, 0xbfb8aa3b, v91
	v_exp_f32_e32 v90, v90
	v_exp_f32_e32 v91, v91
	v_pk_add_f32 v[92:93], v[92:93], v[100:101]
	v_add_f32_e32 v90, 1.0, v90
	v_add_f32_e32 v91, 1.0, v91
	v_rcp_f32_e32 v90, v90
	v_rcp_f32_e32 v91, v91
	v_lshlrev_b32_e32 v100, 16, v98
	v_and_b32_e32 v98, 0xffff0000, v98
	v_mul_f32_e32 v90, v90, v100
	v_mul_f32_e32 v91, v91, v98
	v_cvt_pk_bf16_f32 v90, v90, v91
	v_mul_f32_e32 v91, 0xbfb8aa3b, v92
	v_exp_f32_e32 v91, v91
	v_mul_f32_e32 v92, 0xbfb8aa3b, v93
	v_exp_f32_e32 v92, v92
	v_lshlrev_b32_e32 v101, 16, v99
	v_add_f32_e32 v91, 1.0, v91
	v_rcp_f32_e32 v91, v91
	v_add_f32_e32 v92, 1.0, v92
	v_rcp_f32_e32 v92, v92
	v_and_b32_e32 v99, 0xffff0000, v99
	v_mul_f32_e32 v91, v91, v101
	v_mul_f32_e32 v92, v92, v99
	v_cvt_pk_bf16_f32 v91, v91, v92
	global_store_dwordx2 v[96:97], v[90:91], off offset:2080
	s_waitcnt vmcnt(23)
	v_mov_b64_e32 v[90:91], v[164:165]
	v_mov_b64_e32 v[92:93], v[166:167]
	v_pk_add_f32 v[86:87], v[86:87], v[90:91]
	s_waitcnt vmcnt(3)
	v_mov_b64_e32 v[90:91], v[176:177]
	v_mul_f32_e32 v86, 0xbfb8aa3b, v86
	v_mul_f32_e32 v87, 0xbfb8aa3b, v87
	v_exp_f32_e32 v86, v86
	v_exp_f32_e32 v87, v87
	v_pk_add_f32 v[88:89], v[88:89], v[92:93]
	v_add_f32_e32 v86, 1.0, v86
	v_add_f32_e32 v87, 1.0, v87
	v_rcp_f32_e32 v86, v86
	v_rcp_f32_e32 v87, v87
	v_lshlrev_b32_e32 v92, 16, v90
	v_and_b32_e32 v90, 0xffff0000, v90
	v_mul_f32_e32 v86, v86, v92
	v_mul_f32_e32 v87, v87, v90
	v_cvt_pk_bf16_f32 v86, v86, v87
	v_mul_f32_e32 v87, 0xbfb8aa3b, v88
	v_exp_f32_e32 v87, v87
	v_mul_f32_e32 v88, 0xbfb8aa3b, v89
	v_exp_f32_e32 v88, v88
	v_lshlrev_b32_e32 v93, 16, v91
	v_add_f32_e32 v87, 1.0, v87
	v_rcp_f32_e32 v87, v87
	v_add_f32_e32 v88, 1.0, v88
	v_rcp_f32_e32 v88, v88
	v_and_b32_e32 v91, 0xffff0000, v91
	v_mul_f32_e32 v87, v87, v93
	v_mul_f32_e32 v88, v88, v91
	v_cvt_pk_bf16_f32 v87, v87, v88
	global_store_dwordx2 v[96:97], v[86:87], off offset:2304
	s_waitcnt vmcnt(23)
	v_mov_b64_e32 v[86:87], v[168:169]
	v_mov_b64_e32 v[88:89], v[170:171]
	v_pk_add_f32 v[82:83], v[82:83], v[86:87]
	s_waitcnt vmcnt(3)
	v_mov_b64_e32 v[86:87], v[178:179]
	v_mul_f32_e32 v82, 0xbfb8aa3b, v82
	v_mul_f32_e32 v83, 0xbfb8aa3b, v83
	v_exp_f32_e32 v82, v82
	v_exp_f32_e32 v83, v83
	v_pk_add_f32 v[84:85], v[84:85], v[88:89]
	v_add_f32_e32 v82, 1.0, v82
	v_add_f32_e32 v83, 1.0, v83
	v_rcp_f32_e32 v82, v82
	v_rcp_f32_e32 v83, v83
	v_lshlrev_b32_e32 v88, 16, v86
	v_and_b32_e32 v86, 0xffff0000, v86
	v_mul_f32_e32 v82, v82, v88
	v_mul_f32_e32 v83, v83, v86
	v_cvt_pk_bf16_f32 v82, v82, v83
	v_mul_f32_e32 v83, 0xbfb8aa3b, v84
	v_exp_f32_e32 v83, v83
	v_mul_f32_e32 v84, 0xbfb8aa3b, v85
	v_exp_f32_e32 v84, v84
	v_lshlrev_b32_e32 v89, 16, v87
	v_add_f32_e32 v83, 1.0, v83
	v_rcp_f32_e32 v83, v83
	v_add_f32_e32 v84, 1.0, v84
	v_rcp_f32_e32 v84, v84
	v_and_b32_e32 v87, 0xffff0000, v87
	v_mul_f32_e32 v83, v83, v89
	v_mul_f32_e32 v84, v84, v87
	v_cvt_pk_bf16_f32 v83, v83, v84
	global_store_dwordx2 v[96:97], v[82:83], off offset:2336
	s_waitcnt vmcnt(27)
	v_mov_b64_e32 v[84:85], v[156:157]
	v_mov_b64_e32 v[86:87], v[158:159]
	v_add_u32_e32 v82, 48, v140
	v_ashrrev_i32_e32 v83, 31, v82
	v_lshlrev_b64 v[88:89], 10, v[82:83]
	v_lshlrev_b64 v[82:83], 12, v[82:83]
	v_pk_add_f32 v[84:85], v[78:79], v[84:85]
	v_lshl_add_u64 v[78:79], s[8:9], 0, v[88:89]
	v_lshl_add_u64 v[78:79], v[78:79], 0, v[126:127]
	v_pk_add_f32 v[80:81], v[80:81], v[86:87]
	global_load_dwordx2 v[180:181], v[78:79], off
	global_load_dwordx2 v[182:183], v[78:79], off offset:32
	global_load_dwordx2 v[184:185], v[78:79], off offset:256
	global_load_dwordx2 v[186:187], v[78:79], off offset:288
	s_waitcnt vmcnt(3)
	v_mov_b64_e32 v[86:87], v[180:181]
	v_mul_f32_e32 v84, 0xbfb8aa3b, v84
	v_mul_f32_e32 v85, 0xbfb8aa3b, v85
	v_mul_f32_e32 v80, 0xbfb8aa3b, v80
	v_mul_f32_e32 v81, 0xbfb8aa3b, v81
	v_exp_f32_e32 v84, v84
	v_exp_f32_e32 v85, v85
	v_exp_f32_e32 v80, v80
	v_exp_f32_e32 v81, v81
	v_add_f32_e32 v84, 1.0, v84
	v_add_f32_e32 v85, 1.0, v85
	v_add_f32_e32 v80, 1.0, v80
	v_add_f32_e32 v81, 1.0, v81
	v_rcp_f32_e32 v84, v84
	v_rcp_f32_e32 v85, v85
	v_rcp_f32_e32 v80, v80
	v_rcp_f32_e32 v81, v81
	v_lshlrev_b32_e32 v88, 16, v86
	v_and_b32_e32 v86, 0xffff0000, v86
	v_lshlrev_b32_e32 v89, 16, v87
	v_and_b32_e32 v87, 0xffff0000, v87
	v_mul_f32_e32 v84, v84, v88
	v_mul_f32_e32 v85, v85, v86
	v_mul_f32_e32 v80, v80, v89
	v_mul_f32_e32 v81, v81, v87
	v_cvt_pk_bf16_f32 v84, v84, v85
	v_cvt_pk_bf16_f32 v85, v80, v81
	v_lshl_add_u64 v[80:81], s[12:13], 0, v[82:83]
	v_lshl_add_u64 v[80:81], v[80:81], 0, v[126:127]
	global_store_dwordx2 v[80:81], v[84:85], off offset:2048
	s_waitcnt vmcnt(31)
; __device__ __forceinline__ unsigned cvtpk(float lo, float hi) { unsigned r; asm volatile("v_cvt_pk_bf16_f32 %0, %1, %2" : "=v"(r) : "v"(lo), "v"(hi)); return r; }
; __device__ __forceinline__ float sigmoidf_(float x) { return __builtin_amdgcn_rcpf(1.f + __builtin_amdgcn_exp2f(x * -1.4426950408889634f)); }
;   __device__ __forceinline__ void operator()(const Acc& acc, const gm::Unit& u, int wr, int wc, int fr, int fq) const { const int pm = u.pm, pn = u.pn;
;     ...
;       for (int m = 0; m < 4; ++m) { const int row = pm * 256 + ai * 128 + wr * 64 + m * 16 + fr;
; #pragma unroll
;         for (int bj = 0; bj < 2; ++bj)
; #pragma unroll
;           for (int n = 0; n < 2; ++n) { const int col = pn * 256 + bj * 128 + wc * 32 + n * 16 + fq * 4; const f32x4 z = acc[ai][bj][m][n] + *(const f32x4*)(bg + col);
;             const u32x2 gw = *(const u32x2*)(Gg + (size_t)row * 512 + col);
;             const float g0 = __uint_as_float(gw[0] << 16), g1 = __uint_as_float(gw[0] & 0xffff0000u), g2 = __uint_as_float(gw[1] << 16), g3 = __uint_as_float(gw[1] & 0xffff0000u);
;             u32x2 w = {cvtpk(g0 * sigmoidf_(z[0]), g1 * sigmoidf_(z[1])), cvtpk(g2 * sigmoidf_(z[2]), g3 * sigmoidf_(z[3]))};
;             *(u32x2*)(Cat + (size_t)row * DM + 1024 + col) = w; } }
	v_mov_b64_e32 v[82:83], v[160:161]
	v_mov_b64_e32 v[84:85], v[162:163]
	v_pk_add_f32 v[74:75], v[74:75], v[82:83]
	s_waitcnt vmcnt(3)
	v_mov_b64_e32 v[82:83], v[182:183]
	v_mul_f32_e32 v74, 0xbfb8aa3b, v74
	v_mul_f32_e32 v75, 0xbfb8aa3b, v75
	v_exp_f32_e32 v74, v74
	v_exp_f32_e32 v75, v75
	v_pk_add_f32 v[76:77], v[76:77], v[84:85]
	v_add_f32_e32 v74, 1.0, v74
	v_add_f32_e32 v75, 1.0, v75
	v_rcp_f32_e32 v74, v74
	v_rcp_f32_e32 v75, v75
	v_lshlrev_b32_e32 v84, 16, v82
	v_and_b32_e32 v82, 0xffff0000, v82
	v_mul_f32_e32 v74, v74, v84
	v_mul_f32_e32 v75, v75, v82
	v_cvt_pk_bf16_f32 v74, v74, v75
	v_mul_f32_e32 v75, 0xbfb8aa3b, v76
	v_exp_f32_e32 v75, v75
	v_mul_f32_e32 v76, 0xbfb8aa3b, v77
	v_exp_f32_e32 v76, v76
	v_lshlrev_b32_e32 v85, 16, v83
	v_add_f32_e32 v75, 1.0, v75
	v_rcp_f32_e32 v75, v75
	v_add_f32_e32 v76, 1.0, v76
	v_rcp_f32_e32 v76, v76
	v_and_b32_e32 v83, 0xffff0000, v83
	v_mul_f32_e32 v75, v75, v85
	v_mul_f32_e32 v76, v76, v83
	v_cvt_pk_bf16_f32 v75, v75, v76
	global_store_dwordx2 v[80:81], v[74:75], off offset:2080
	s_waitcnt vmcnt(31)
	v_mov_b64_e32 v[74:75], v[164:165]
	v_mov_b64_e32 v[76:77], v[166:167]
	v_pk_add_f32 v[70:71], v[70:71], v[74:75]
	s_waitcnt vmcnt(3)
	v_mov_b64_e32 v[74:75], v[184:185]
	v_mul_f32_e32 v70, 0xbfb8aa3b, v70
	v_mul_f32_e32 v71, 0xbfb8aa3b, v71
	v_exp_f32_e32 v70, v70
	v_exp_f32_e32 v71, v71
	v_pk_add_f32 v[72:73], v[72:73], v[76:77]
	v_add_f32_e32 v70, 1.0, v70
	v_add_f32_e32 v71, 1.0, v71
	v_rcp_f32_e32 v70, v70
	v_rcp_f32_e32 v71, v71
	v_lshlrev_b32_e32 v76, 16, v74
	v_and_b32_e32 v74, 0xffff0000, v74
	v_mul_f32_e32 v70, v70, v76
	v_mul_f32_e32 v71, v71, v74
	v_cvt_pk_bf16_f32 v70, v70, v71
	v_mul_f32_e32 v71, 0xbfb8aa3b, v72
	v_exp_f32_e32 v71, v71
	v_mul_f32_e32 v72, 0xbfb8aa3b, v73
	v_exp_f32_e32 v72, v72
	v_lshlrev_b32_e32 v77, 16, v75
	v_add_f32_e32 v71, 1.0, v71
	v_rcp_f32_e32 v71, v71
	v_add_f32_e32 v72, 1.0, v72
	v_rcp_f32_e32 v72, v72
	v_and_b32_e32 v75, 0xffff0000, v75
	v_mul_f32_e32 v71, v71, v77
	v_mul_f32_e32 v72, v72, v75
	v_cvt_pk_bf16_f32 v71, v71, v72
	global_store_dwordx2 v[80:81], v[70:71], off offset:2304
	s_waitcnt vmcnt(31)
	v_mov_b64_e32 v[70:71], v[168:169]
	v_mov_b64_e32 v[72:73], v[170:171]
	v_pk_add_f32 v[66:67], v[66:67], v[70:71]
	s_waitcnt vmcnt(3)
	v_mov_b64_e32 v[70:71], v[186:187]
	v_mul_f32_e32 v66, 0xbfb8aa3b, v66
	v_mul_f32_e32 v67, 0xbfb8aa3b, v67
	v_exp_f32_e32 v66, v66
	v_exp_f32_e32 v67, v67
	v_pk_add_f32 v[68:69], v[68:69], v[72:73]
	v_add_f32_e32 v66, 1.0, v66
	v_add_f32_e32 v67, 1.0, v67
	v_rcp_f32_e32 v66, v66
	v_rcp_f32_e32 v67, v67
	v_lshlrev_b32_e32 v72, 16, v70
	v_and_b32_e32 v70, 0xffff0000, v70
	v_mul_f32_e32 v66, v66, v72
	v_mul_f32_e32 v67, v67, v70
	v_cvt_pk_bf16_f32 v66, v66, v67
	v_mul_f32_e32 v67, 0xbfb8aa3b, v68
	v_exp_f32_e32 v67, v67
	v_mul_f32_e32 v68, 0xbfb8aa3b, v69
	v_exp_f32_e32 v68, v68
	v_lshlrev_b32_e32 v73, 16, v71
	v_add_f32_e32 v67, 1.0, v67
	v_rcp_f32_e32 v67, v67
	v_add_f32_e32 v68, 1.0, v68
	v_rcp_f32_e32 v68, v68
	v_and_b32_e32 v71, 0xffff0000, v71
	v_mul_f32_e32 v67, v67, v73
	v_mul_f32_e32 v68, v68, v71
	v_cvt_pk_bf16_f32 v67, v67, v68
	global_store_dwordx2 v[80:81], v[66:67], off offset:2336
	s_waitcnt vmcnt(35)
	v_mov_b64_e32 v[68:69], v[156:157]
	v_mov_b64_e32 v[70:71], v[158:159]
	v_add_u32_e32 v66, 0x80, v140
	v_ashrrev_i32_e32 v67, 31, v66
	v_lshlrev_b64 v[72:73], 10, v[66:67]
	v_lshlrev_b64 v[66:67], 12, v[66:67]
	v_pk_add_f32 v[68:69], v[62:63], v[68:69]
	v_lshl_add_u64 v[62:63], s[8:9], 0, v[72:73]
	v_lshl_add_u64 v[62:63], v[62:63], 0, v[126:127]
	v_pk_add_f32 v[64:65], v[64:65], v[70:71]
	global_load_dwordx2 v[172:173], v[62:63], off
	global_load_dwordx2 v[174:175], v[62:63], off offset:32
	global_load_dwordx2 v[176:177], v[62:63], off offset:256
	global_load_dwordx2 v[178:179], v[62:63], off offset:288
	s_waitcnt vmcnt(3)
	v_mov_b64_e32 v[70:71], v[172:173]
	v_mul_f32_e32 v68, 0xbfb8aa3b, v68
	v_mul_f32_e32 v69, 0xbfb8aa3b, v69
	v_mul_f32_e32 v64, 0xbfb8aa3b, v64
	v_mul_f32_e32 v65, 0xbfb8aa3b, v65
	v_exp_f32_e32 v68, v68
	v_exp_f32_e32 v69, v69
	v_exp_f32_e32 v64, v64
	v_exp_f32_e32 v65, v65
	v_add_f32_e32 v68, 1.0, v68
	v_add_f32_e32 v69, 1.0, v69
	v_add_f32_e32 v64, 1.0, v64
	v_add_f32_e32 v65, 1.0, v65
	v_rcp_f32_e32 v68, v68
	v_rcp_f32_e32 v69, v69
	v_rcp_f32_e32 v64, v64
	v_rcp_f32_e32 v65, v65
	v_lshlrev_b32_e32 v72, 16, v70
	v_and_b32_e32 v70, 0xffff0000, v70
	v_lshlrev_b32_e32 v73, 16, v71
	v_and_b32_e32 v71, 0xffff0000, v71
	v_mul_f32_e32 v68, v68, v72
	v_mul_f32_e32 v69, v69, v70
	v_mul_f32_e32 v64, v64, v73
	v_mul_f32_e32 v65, v65, v71
	v_cvt_pk_bf16_f32 v68, v68, v69
	v_cvt_pk_bf16_f32 v69, v64, v65
	v_lshl_add_u64 v[64:65], s[12:13], 0, v[66:67]
	v_lshl_add_u64 v[64:65], v[64:65], 0, v[126:127]
	global_store_dwordx2 v[64:65], v[68:69], off offset:2048
	s_waitcnt vmcnt(39)
	v_mov_b64_e32 v[66:67], v[160:161]
	v_mov_b64_e32 v[68:69], v[162:163]
	v_pk_add_f32 v[58:59], v[58:59], v[66:67]
	s_waitcnt vmcnt(3)
	v_mov_b64_e32 v[66:67], v[174:175]
	v_mul_f32_e32 v58, 0xbfb8aa3b, v58
	v_mul_f32_e32 v59, 0xbfb8aa3b, v59
	v_exp_f32_e32 v58, v58
	v_exp_f32_e32 v59, v59
	v_pk_add_f32 v[60:61], v[60:61], v[68:69]
	v_add_f32_e32 v58, 1.0, v58
	v_add_f32_e32 v59, 1.0, v59
	v_rcp_f32_e32 v58, v58
	v_rcp_f32_e32 v59, v59
	v_lshlrev_b32_e32 v68, 16, v66
	v_and_b32_e32 v66, 0xffff0000, v66
	v_mul_f32_e32 v58, v58, v68
	v_mul_f32_e32 v59, v59, v66
	v_cvt_pk_bf16_f32 v58, v58, v59
	v_mul_f32_e32 v59, 0xbfb8aa3b, v60
	v_exp_f32_e32 v59, v59
	v_mul_f32_e32 v60, 0xbfb8aa3b, v61
	v_exp_f32_e32 v60, v60
	v_lshlrev_b32_e32 v69, 16, v67
	v_add_f32_e32 v59, 1.0, v59
	v_rcp_f32_e32 v59, v59
	v_add_f32_e32 v60, 1.0, v60
	v_rcp_f32_e32 v60, v60
	v_and_b32_e32 v67, 0xffff0000, v67
	v_mul_f32_e32 v59, v59, v69
	v_mul_f32_e32 v60, v60, v67
	v_cvt_pk_bf16_f32 v59, v59, v60
	global_store_dwordx2 v[64:65], v[58:59], off offset:2080
	s_waitcnt vmcnt(39)
; __device__ __forceinline__ unsigned cvtpk(float lo, float hi) { unsigned r; asm volatile("v_cvt_pk_bf16_f32 %0, %1, %2" : "=v"(r) : "v"(lo), "v"(hi)); return r; }
; __device__ __forceinline__ float sigmoidf_(float x) { return __builtin_amdgcn_rcpf(1.f + __builtin_amdgcn_exp2f(x * -1.4426950408889634f)); }
;   __device__ __forceinline__ void operator()(const Acc& acc, const gm::Unit& u, int wr, int wc, int fr, int fq) const { const int pm = u.pm, pn = u.pn;
;     ...
;       for (int m = 0; m < 4; ++m) { const int row = pm * 256 + ai * 128 + wr * 64 + m * 16 + fr;
; #pragma unroll
;         for (int bj = 0; bj < 2; ++bj)
; #pragma unroll
;           for (int n = 0; n < 2; ++n) { const int col = pn * 256 + bj * 128 + wc * 32 + n * 16 + fq * 4; const f32x4 z = acc[ai][bj][m][n] + *(const f32x4*)(bg + col);
;             const u32x2 gw = *(const u32x2*)(Gg + (size_t)row * 512 + col);
;             const float g0 = __uint_as_float(gw[0] << 16), g1 = __uint_as_float(gw[0] & 0xffff0000u), g2 = __uint_as_float(gw[1] << 16), g3 = __uint_as_float(gw[1] & 0xffff0000u);
;             u32x2 w = {cvtpk(g0 * sigmoidf_(z[0]), g1 * sigmoidf_(z[1])), cvtpk(g2 * sigmoidf_(z[2]), g3 * sigmoidf_(z[3]))};
;             *(u32x2*)(Cat + (size_t)row * DM + 1024 + col) = w; } }
	v_mov_b64_e32 v[58:59], v[164:165]
	v_mov_b64_e32 v[60:61], v[166:167]
	v_pk_add_f32 v[54:55], v[54:55], v[58:59]
	s_waitcnt vmcnt(3)
	v_mov_b64_e32 v[58:59], v[176:177]
	v_mul_f32_e32 v54, 0xbfb8aa3b, v54
	v_mul_f32_e32 v55, 0xbfb8aa3b, v55
	v_exp_f32_e32 v54, v54
	v_exp_f32_e32 v55, v55
	v_pk_add_f32 v[56:57], v[56:57], v[60:61]
	v_add_f32_e32 v54, 1.0, v54
	v_add_f32_e32 v55, 1.0, v55
	v_rcp_f32_e32 v54, v54
	v_rcp_f32_e32 v55, v55
	v_lshlrev_b32_e32 v60, 16, v58
	v_and_b32_e32 v58, 0xffff0000, v58
	v_mul_f32_e32 v54, v54, v60
	v_mul_f32_e32 v55, v55, v58
	v_cvt_pk_bf16_f32 v54, v54, v55
	v_mul_f32_e32 v55, 0xbfb8aa3b, v56
	v_exp_f32_e32 v55, v55
	v_mul_f32_e32 v56, 0xbfb8aa3b, v57
	v_exp_f32_e32 v56, v56
	v_lshlrev_b32_e32 v61, 16, v59
	v_add_f32_e32 v55, 1.0, v55
	v_rcp_f32_e32 v55, v55
	v_add_f32_e32 v56, 1.0, v56
	v_rcp_f32_e32 v56, v56
	v_and_b32_e32 v59, 0xffff0000, v59
	v_mul_f32_e32 v55, v55, v61
	v_mul_f32_e32 v56, v56, v59
	v_cvt_pk_bf16_f32 v55, v55, v56
	global_store_dwordx2 v[64:65], v[54:55], off offset:2304
	s_waitcnt vmcnt(39)
	v_mov_b64_e32 v[54:55], v[168:169]
	v_mov_b64_e32 v[56:57], v[170:171]
	v_pk_add_f32 v[50:51], v[50:51], v[54:55]
	s_waitcnt vmcnt(3)
	v_mov_b64_e32 v[54:55], v[178:179]
	v_mul_f32_e32 v50, 0xbfb8aa3b, v50
	v_mul_f32_e32 v51, 0xbfb8aa3b, v51
	v_exp_f32_e32 v50, v50
	v_exp_f32_e32 v51, v51
	v_pk_add_f32 v[52:53], v[52:53], v[56:57]
	v_add_f32_e32 v50, 1.0, v50
	v_add_f32_e32 v51, 1.0, v51
	v_rcp_f32_e32 v50, v50
	v_rcp_f32_e32 v51, v51
	v_lshlrev_b32_e32 v56, 16, v54
	v_and_b32_e32 v54, 0xffff0000, v54
	v_mul_f32_e32 v50, v50, v56
	v_mul_f32_e32 v51, v51, v54
	v_cvt_pk_bf16_f32 v50, v50, v51
	v_mul_f32_e32 v51, 0xbfb8aa3b, v52
	v_exp_f32_e32 v51, v51
	v_mul_f32_e32 v52, 0xbfb8aa3b, v53
	v_exp_f32_e32 v52, v52
	v_lshlrev_b32_e32 v57, 16, v55
	v_add_f32_e32 v51, 1.0, v51
	v_rcp_f32_e32 v51, v51
	v_add_f32_e32 v52, 1.0, v52
	v_rcp_f32_e32 v52, v52
	v_and_b32_e32 v55, 0xffff0000, v55
	v_mul_f32_e32 v51, v51, v57
	v_mul_f32_e32 v52, v52, v55
	v_cvt_pk_bf16_f32 v51, v51, v52
	global_store_dwordx2 v[64:65], v[50:51], off offset:2336
	s_waitcnt vmcnt(43)
	v_mov_b64_e32 v[52:53], v[156:157]
	v_mov_b64_e32 v[54:55], v[158:159]
	v_add_u32_e32 v50, 0x90, v140
	v_ashrrev_i32_e32 v51, 31, v50
	v_lshlrev_b64 v[56:57], 10, v[50:51]
	v_lshlrev_b64 v[50:51], 12, v[50:51]
	v_pk_add_f32 v[52:53], v[46:47], v[52:53]
	v_lshl_add_u64 v[46:47], s[8:9], 0, v[56:57]
	v_lshl_add_u64 v[46:47], v[46:47], 0, v[126:127]
	v_pk_add_f32 v[48:49], v[48:49], v[54:55]
	global_load_dwordx2 v[180:181], v[46:47], off
	global_load_dwordx2 v[182:183], v[46:47], off offset:32
	global_load_dwordx2 v[184:185], v[46:47], off offset:256
	global_load_dwordx2 v[186:187], v[46:47], off offset:288
	s_waitcnt vmcnt(3)
	v_mov_b64_e32 v[54:55], v[180:181]
	v_mul_f32_e32 v52, 0xbfb8aa3b, v52
	v_mul_f32_e32 v53, 0xbfb8aa3b, v53
	v_mul_f32_e32 v48, 0xbfb8aa3b, v48
	v_mul_f32_e32 v49, 0xbfb8aa3b, v49
	v_exp_f32_e32 v52, v52
	v_exp_f32_e32 v53, v53
	v_exp_f32_e32 v48, v48
	v_exp_f32_e32 v49, v49
	v_add_f32_e32 v52, 1.0, v52
	v_add_f32_e32 v53, 1.0, v53
	v_add_f32_e32 v48, 1.0, v48
	v_add_f32_e32 v49, 1.0, v49
	v_rcp_f32_e32 v52, v52
	v_rcp_f32_e32 v53, v53
	v_rcp_f32_e32 v48, v48
	v_rcp_f32_e32 v49, v49
	v_lshlrev_b32_e32 v56, 16, v54
	v_and_b32_e32 v54, 0xffff0000, v54
	v_lshlrev_b32_e32 v57, 16, v55
	v_and_b32_e32 v55, 0xffff0000, v55
	v_mul_f32_e32 v52, v52, v56
	v_mul_f32_e32 v53, v53, v54
	v_mul_f32_e32 v48, v48, v57
	v_mul_f32_e32 v49, v49, v55
	v_cvt_pk_bf16_f32 v52, v52, v53
	v_cvt_pk_bf16_f32 v53, v48, v49
	v_lshl_add_u64 v[48:49], s[12:13], 0, v[50:51]
	v_lshl_add_u64 v[48:49], v[48:49], 0, v[126:127]
	global_store_dwordx2 v[48:49], v[52:53], off offset:2048
	s_waitcnt vmcnt(47)
	v_mov_b64_e32 v[50:51], v[160:161]
	v_mov_b64_e32 v[52:53], v[162:163]
	v_pk_add_f32 v[42:43], v[42:43], v[50:51]
	s_waitcnt vmcnt(3)
	v_mov_b64_e32 v[50:51], v[182:183]
	v_mul_f32_e32 v42, 0xbfb8aa3b, v42
	v_mul_f32_e32 v43, 0xbfb8aa3b, v43
	v_exp_f32_e32 v42, v42
	v_exp_f32_e32 v43, v43
	v_pk_add_f32 v[44:45], v[44:45], v[52:53]
	v_add_f32_e32 v42, 1.0, v42
	v_add_f32_e32 v43, 1.0, v43
	v_rcp_f32_e32 v42, v42
	v_rcp_f32_e32 v43, v43
	v_lshlrev_b32_e32 v52, 16, v50
	v_and_b32_e32 v50, 0xffff0000, v50
	v_mul_f32_e32 v42, v42, v52
	v_mul_f32_e32 v43, v43, v50
	v_cvt_pk_bf16_f32 v42, v42, v43
	v_mul_f32_e32 v43, 0xbfb8aa3b, v44
	v_exp_f32_e32 v43, v43
	v_mul_f32_e32 v44, 0xbfb8aa3b, v45
	v_exp_f32_e32 v44, v44
	v_lshlrev_b32_e32 v53, 16, v51
	v_add_f32_e32 v43, 1.0, v43
	v_rcp_f32_e32 v43, v43
	v_add_f32_e32 v44, 1.0, v44
	v_rcp_f32_e32 v44, v44
	v_and_b32_e32 v51, 0xffff0000, v51
	v_mul_f32_e32 v43, v43, v53
	v_mul_f32_e32 v44, v44, v51
	v_cvt_pk_bf16_f32 v43, v43, v44
	global_store_dwordx2 v[48:49], v[42:43], off offset:2080
	s_waitcnt vmcnt(47)
	v_mov_b64_e32 v[42:43], v[164:165]
	v_mov_b64_e32 v[44:45], v[166:167]
	v_pk_add_f32 v[38:39], v[38:39], v[42:43]
	s_waitcnt vmcnt(3)
	v_mov_b64_e32 v[42:43], v[184:185]
	v_mul_f32_e32 v38, 0xbfb8aa3b, v38
	v_mul_f32_e32 v39, 0xbfb8aa3b, v39
	v_exp_f32_e32 v38, v38
	v_exp_f32_e32 v39, v39
	v_pk_add_f32 v[40:41], v[40:41], v[44:45]
	v_add_f32_e32 v38, 1.0, v38
	v_add_f32_e32 v39, 1.0, v39
	v_rcp_f32_e32 v38, v38
	v_rcp_f32_e32 v39, v39
	v_lshlrev_b32_e32 v44, 16, v42
	v_and_b32_e32 v42, 0xffff0000, v42
	v_mul_f32_e32 v38, v38, v44
	v_mul_f32_e32 v39, v39, v42
	v_cvt_pk_bf16_f32 v38, v38, v39
	v_mul_f32_e32 v39, 0xbfb8aa3b, v40
	v_exp_f32_e32 v39, v39
	v_mul_f32_e32 v40, 0xbfb8aa3b, v41
	v_exp_f32_e32 v40, v40
	v_lshlrev_b32_e32 v45, 16, v43
	v_add_f32_e32 v39, 1.0, v39
	v_rcp_f32_e32 v39, v39
	v_add_f32_e32 v40, 1.0, v40
	v_rcp_f32_e32 v40, v40
	v_and_b32_e32 v43, 0xffff0000, v43
	v_mul_f32_e32 v39, v39, v45
	v_mul_f32_e32 v40, v40, v43
	v_cvt_pk_bf16_f32 v39, v39, v40
	global_store_dwordx2 v[48:49], v[38:39], off offset:2304
	s_waitcnt vmcnt(47)
; __device__ __forceinline__ unsigned cvtpk(float lo, float hi) { unsigned r; asm volatile("v_cvt_pk_bf16_f32 %0, %1, %2" : "=v"(r) : "v"(lo), "v"(hi)); return r; }
; __device__ __forceinline__ float sigmoidf_(float x) { return __builtin_amdgcn_rcpf(1.f + __builtin_amdgcn_exp2f(x * -1.4426950408889634f)); }
;   __device__ __forceinline__ void operator()(const Acc& acc, const gm::Unit& u, int wr, int wc, int fr, int fq) const { const int pm = u.pm, pn = u.pn;
;     ...
;       for (int m = 0; m < 4; ++m) { const int row = pm * 256 + ai * 128 + wr * 64 + m * 16 + fr;
; #pragma unroll
;         for (int bj = 0; bj < 2; ++bj)
; #pragma unroll
;           for (int n = 0; n < 2; ++n) { const int col = pn * 256 + bj * 128 + wc * 32 + n * 16 + fq * 4; const f32x4 z = acc[ai][bj][m][n] + *(const f32x4*)(bg + col);
;             const u32x2 gw = *(const u32x2*)(Gg + (size_t)row * 512 + col);
;             const float g0 = __uint_as_float(gw[0] << 16), g1 = __uint_as_float(gw[0] & 0xffff0000u), g2 = __uint_as_float(gw[1] << 16), g3 = __uint_as_float(gw[1] & 0xffff0000u);
;             u32x2 w = {cvtpk(g0 * sigmoidf_(z[0]), g1 * sigmoidf_(z[1])), cvtpk(g2 * sigmoidf_(z[2]), g3 * sigmoidf_(z[3]))};
;             *(u32x2*)(Cat + (size_t)row * DM + 1024 + col) = w; } }
	v_mov_b64_e32 v[38:39], v[168:169]
	v_mov_b64_e32 v[40:41], v[170:171]
	v_pk_add_f32 v[34:35], v[34:35], v[38:39]
	s_waitcnt vmcnt(3)
	v_mov_b64_e32 v[38:39], v[186:187]
	v_mul_f32_e32 v34, 0xbfb8aa3b, v34
	v_mul_f32_e32 v35, 0xbfb8aa3b, v35
	v_exp_f32_e32 v34, v34
	v_exp_f32_e32 v35, v35
	v_pk_add_f32 v[36:37], v[36:37], v[40:41]
	v_add_f32_e32 v34, 1.0, v34
	v_add_f32_e32 v35, 1.0, v35
	v_rcp_f32_e32 v34, v34
	v_rcp_f32_e32 v35, v35
	v_lshlrev_b32_e32 v40, 16, v38
	v_and_b32_e32 v38, 0xffff0000, v38
	v_mul_f32_e32 v34, v34, v40
	v_mul_f32_e32 v35, v35, v38
	v_cvt_pk_bf16_f32 v34, v34, v35
	v_mul_f32_e32 v35, 0xbfb8aa3b, v36
	v_exp_f32_e32 v35, v35
	v_mul_f32_e32 v36, 0xbfb8aa3b, v37
	v_exp_f32_e32 v36, v36
	v_lshlrev_b32_e32 v41, 16, v39
	v_add_f32_e32 v35, 1.0, v35
	v_rcp_f32_e32 v35, v35
	v_add_f32_e32 v36, 1.0, v36
	v_rcp_f32_e32 v36, v36
	v_and_b32_e32 v39, 0xffff0000, v39
	v_mul_f32_e32 v35, v35, v41
	v_mul_f32_e32 v36, v36, v39
	v_cvt_pk_bf16_f32 v35, v35, v36
	global_store_dwordx2 v[48:49], v[34:35], off offset:2336
	s_waitcnt vmcnt(51)
	v_mov_b64_e32 v[36:37], v[156:157]
	v_mov_b64_e32 v[38:39], v[158:159]
	v_add_u32_e32 v34, 0xa0, v140
	v_ashrrev_i32_e32 v35, 31, v34
	v_lshlrev_b64 v[40:41], 10, v[34:35]
	v_lshlrev_b64 v[34:35], 12, v[34:35]
	v_pk_add_f32 v[36:37], v[30:31], v[36:37]
	v_lshl_add_u64 v[30:31], s[8:9], 0, v[40:41]
	v_lshl_add_u64 v[30:31], v[30:31], 0, v[126:127]
	v_pk_add_f32 v[32:33], v[32:33], v[38:39]
	global_load_dwordx2 v[172:173], v[30:31], off
	global_load_dwordx2 v[174:175], v[30:31], off offset:32
	global_load_dwordx2 v[176:177], v[30:31], off offset:256
	global_load_dwordx2 v[178:179], v[30:31], off offset:288
	s_waitcnt vmcnt(3)
	v_mov_b64_e32 v[38:39], v[172:173]
	v_mul_f32_e32 v36, 0xbfb8aa3b, v36
	v_mul_f32_e32 v37, 0xbfb8aa3b, v37
	v_mul_f32_e32 v32, 0xbfb8aa3b, v32
	v_mul_f32_e32 v33, 0xbfb8aa3b, v33
	v_exp_f32_e32 v36, v36
	v_exp_f32_e32 v37, v37
	v_exp_f32_e32 v32, v32
	v_exp_f32_e32 v33, v33
	v_add_f32_e32 v36, 1.0, v36
	v_add_f32_e32 v37, 1.0, v37
	v_add_f32_e32 v32, 1.0, v32
	v_add_f32_e32 v33, 1.0, v33
	v_rcp_f32_e32 v36, v36
	v_rcp_f32_e32 v37, v37
	v_rcp_f32_e32 v32, v32
	v_rcp_f32_e32 v33, v33
	v_lshlrev_b32_e32 v40, 16, v38
	v_and_b32_e32 v38, 0xffff0000, v38
	v_lshlrev_b32_e32 v41, 16, v39
	v_and_b32_e32 v39, 0xffff0000, v39
	v_mul_f32_e32 v36, v36, v40
	v_mul_f32_e32 v37, v37, v38
	v_mul_f32_e32 v32, v32, v41
	v_mul_f32_e32 v33, v33, v39
	v_cvt_pk_bf16_f32 v36, v36, v37
	v_cvt_pk_bf16_f32 v37, v32, v33
	v_lshl_add_u64 v[32:33], s[12:13], 0, v[34:35]
	v_lshl_add_u64 v[32:33], v[32:33], 0, v[126:127]
	global_store_dwordx2 v[32:33], v[36:37], off offset:2048
	s_waitcnt vmcnt(55)
	v_mov_b64_e32 v[34:35], v[160:161]
	v_mov_b64_e32 v[36:37], v[162:163]
	v_pk_add_f32 v[26:27], v[26:27], v[34:35]
	s_waitcnt vmcnt(3)
	v_mov_b64_e32 v[34:35], v[174:175]
	v_mul_f32_e32 v26, 0xbfb8aa3b, v26
	v_mul_f32_e32 v27, 0xbfb8aa3b, v27
	v_exp_f32_e32 v26, v26
	v_exp_f32_e32 v27, v27
	v_pk_add_f32 v[28:29], v[28:29], v[36:37]
	v_add_f32_e32 v26, 1.0, v26
	v_add_f32_e32 v27, 1.0, v27
	v_rcp_f32_e32 v26, v26
	v_rcp_f32_e32 v27, v27
	v_lshlrev_b32_e32 v36, 16, v34
	v_and_b32_e32 v34, 0xffff0000, v34
	v_mul_f32_e32 v26, v26, v36
	v_mul_f32_e32 v27, v27, v34
	v_cvt_pk_bf16_f32 v26, v26, v27
	v_mul_f32_e32 v27, 0xbfb8aa3b, v28
	v_exp_f32_e32 v27, v27
	v_mul_f32_e32 v28, 0xbfb8aa3b, v29
	v_exp_f32_e32 v28, v28
	v_lshlrev_b32_e32 v37, 16, v35
	v_add_f32_e32 v27, 1.0, v27
	v_rcp_f32_e32 v27, v27
	v_add_f32_e32 v28, 1.0, v28
	v_rcp_f32_e32 v28, v28
	v_and_b32_e32 v35, 0xffff0000, v35
	v_mul_f32_e32 v27, v27, v37
	v_mul_f32_e32 v28, v28, v35
	v_cvt_pk_bf16_f32 v27, v27, v28
	global_store_dwordx2 v[32:33], v[26:27], off offset:2080
	s_waitcnt vmcnt(55)
	v_mov_b64_e32 v[26:27], v[164:165]
	v_mov_b64_e32 v[28:29], v[166:167]
	v_pk_add_f32 v[22:23], v[22:23], v[26:27]
	s_waitcnt vmcnt(3)
	v_mov_b64_e32 v[26:27], v[176:177]
	v_mul_f32_e32 v22, 0xbfb8aa3b, v22
	v_mul_f32_e32 v23, 0xbfb8aa3b, v23
	v_exp_f32_e32 v22, v22
	v_exp_f32_e32 v23, v23
	v_pk_add_f32 v[24:25], v[24:25], v[28:29]
	v_add_f32_e32 v22, 1.0, v22
	v_add_f32_e32 v23, 1.0, v23
	v_rcp_f32_e32 v22, v22
	v_rcp_f32_e32 v23, v23
	v_lshlrev_b32_e32 v28, 16, v26
	v_and_b32_e32 v26, 0xffff0000, v26
	v_mul_f32_e32 v22, v22, v28
	v_mul_f32_e32 v23, v23, v26
	v_cvt_pk_bf16_f32 v22, v22, v23
	v_mul_f32_e32 v23, 0xbfb8aa3b, v24
	v_exp_f32_e32 v23, v23
	v_mul_f32_e32 v24, 0xbfb8aa3b, v25
	v_exp_f32_e32 v24, v24
	v_lshlrev_b32_e32 v29, 16, v27
	v_add_f32_e32 v23, 1.0, v23
	v_rcp_f32_e32 v23, v23
	v_add_f32_e32 v24, 1.0, v24
	v_rcp_f32_e32 v24, v24
	v_and_b32_e32 v27, 0xffff0000, v27
	v_mul_f32_e32 v23, v23, v29
	v_mul_f32_e32 v24, v24, v27
	v_cvt_pk_bf16_f32 v23, v23, v24
	global_store_dwordx2 v[32:33], v[22:23], off offset:2304
	s_waitcnt vmcnt(55)
	v_mov_b64_e32 v[22:23], v[168:169]
	v_mov_b64_e32 v[24:25], v[170:171]
	v_pk_add_f32 v[18:19], v[18:19], v[22:23]
	s_waitcnt vmcnt(3)
; __device__ __forceinline__ unsigned cvtpk(float lo, float hi) { unsigned r; asm volatile("v_cvt_pk_bf16_f32 %0, %1, %2" : "=v"(r) : "v"(lo), "v"(hi)); return r; }
; __device__ __forceinline__ float sigmoidf_(float x) { return __builtin_amdgcn_rcpf(1.f + __builtin_amdgcn_exp2f(x * -1.4426950408889634f)); }
; #define PG8_BAR __builtin_amdgcn_s_barrier()
;     ...
;     if (!has_next) break;
; #pragma unroll
;     for (int a = 0; a < 2; ++a)
; #pragma unroll
;       for (int b = 0; b < 2; ++b)
; #pragma unroll
;         for (int m = 0; m < 4; ++m)
; #pragma unroll
;           for (int n = 0; n < 2; ++n) acc[a][b][m][n] = (f32x4){0.f, 0.f, 0.f, 0.f};
;     cur = nxt; cA = nA; cB = nB; ++ui;
;     if (wr == 1) PG8_BAR;
;   __device__ __forceinline__ void operator()(const Acc& acc, const gm::Unit& u, int wr, int wc, int fr, int fq) const { const int pm = u.pm, pn = u.pn;
;     ...
;       for (int m = 0; m < 4; ++m) { const int row = pm * 256 + ai * 128 + wr * 64 + m * 16 + fr;
; #pragma unroll
;         for (int bj = 0; bj < 2; ++bj)
; #pragma unroll
;           for (int n = 0; n < 2; ++n) { const int col = pn * 256 + bj * 128 + wc * 32 + n * 16 + fq * 4; const f32x4 z = acc[ai][bj][m][n] + *(const f32x4*)(bg + col);
;             const u32x2 gw = *(const u32x2*)(Gg + (size_t)row * 512 + col);
;             const float g0 = __uint_as_float(gw[0] << 16), g1 = __uint_as_float(gw[0] & 0xffff0000u), g2 = __uint_as_float(gw[1] << 16), g3 = __uint_as_float(gw[1] & 0xffff0000u);
;             u32x2 w = {cvtpk(g0 * sigmoidf_(z[0]), g1 * sigmoidf_(z[1])), cvtpk(g2 * sigmoidf_(z[2]), g3 * sigmoidf_(z[3]))};
;             *(u32x2*)(Cat + (size_t)row * DM + 1024 + col) = w; } }
	v_mov_b64_e32 v[22:23], v[178:179]
	v_mul_f32_e32 v18, 0xbfb8aa3b, v18
	v_mul_f32_e32 v19, 0xbfb8aa3b, v19
	v_exp_f32_e32 v18, v18
	v_exp_f32_e32 v19, v19
	v_pk_add_f32 v[20:21], v[20:21], v[24:25]
	v_add_f32_e32 v18, 1.0, v18
	v_add_f32_e32 v19, 1.0, v19
	v_rcp_f32_e32 v18, v18
	v_rcp_f32_e32 v19, v19
	v_lshlrev_b32_e32 v24, 16, v22
	v_and_b32_e32 v22, 0xffff0000, v22
	v_mul_f32_e32 v18, v18, v24
	v_mul_f32_e32 v19, v19, v22
	v_cvt_pk_bf16_f32 v18, v18, v19
	v_mul_f32_e32 v19, 0xbfb8aa3b, v20
	v_exp_f32_e32 v19, v19
	v_mul_f32_e32 v20, 0xbfb8aa3b, v21
	v_exp_f32_e32 v20, v20
	v_lshlrev_b32_e32 v25, 16, v23
	v_add_f32_e32 v19, 1.0, v19
	v_rcp_f32_e32 v19, v19
	v_add_f32_e32 v20, 1.0, v20
	v_rcp_f32_e32 v20, v20
	v_and_b32_e32 v23, 0xffff0000, v23
	v_mul_f32_e32 v19, v19, v25
	v_mul_f32_e32 v20, v20, v23
	v_cvt_pk_bf16_f32 v19, v19, v20
	global_store_dwordx2 v[32:33], v[18:19], off offset:2336
	s_waitcnt vmcnt(59)
	v_mov_b64_e32 v[20:21], v[156:157]
	v_mov_b64_e32 v[22:23], v[158:159]
	v_add_u32_e32 v18, 0xb0, v140
	v_ashrrev_i32_e32 v19, 31, v18
	v_lshlrev_b64 v[24:25], 10, v[18:19]
	v_lshlrev_b64 v[18:19], 12, v[18:19]
	v_pk_add_f32 v[20:21], v[14:15], v[20:21]
	v_lshl_add_u64 v[14:15], s[8:9], 0, v[24:25]
	v_lshl_add_u64 v[14:15], v[14:15], 0, v[126:127]
	v_pk_add_f32 v[16:17], v[16:17], v[22:23]
	global_load_dwordx2 v[180:181], v[14:15], off
	global_load_dwordx2 v[182:183], v[14:15], off offset:32
	global_load_dwordx2 v[184:185], v[14:15], off offset:256
	global_load_dwordx2 v[186:187], v[14:15], off offset:288
	s_waitcnt vmcnt(3)
	v_mov_b64_e32 v[22:23], v[180:181]
	v_mul_f32_e32 v20, 0xbfb8aa3b, v20
	v_mul_f32_e32 v21, 0xbfb8aa3b, v21
	v_mul_f32_e32 v16, 0xbfb8aa3b, v16
	v_mul_f32_e32 v17, 0xbfb8aa3b, v17
	v_exp_f32_e32 v20, v20
	v_exp_f32_e32 v21, v21
	v_exp_f32_e32 v16, v16
	v_exp_f32_e32 v17, v17
	v_add_f32_e32 v20, 1.0, v20
	v_add_f32_e32 v21, 1.0, v21
	v_add_f32_e32 v16, 1.0, v16
	v_add_f32_e32 v17, 1.0, v17
	v_rcp_f32_e32 v20, v20
	v_rcp_f32_e32 v21, v21
	v_rcp_f32_e32 v16, v16
	v_rcp_f32_e32 v17, v17
	v_lshlrev_b32_e32 v24, 16, v22
	v_and_b32_e32 v22, 0xffff0000, v22
	v_lshlrev_b32_e32 v25, 16, v23
	v_and_b32_e32 v23, 0xffff0000, v23
	v_mul_f32_e32 v20, v20, v24
	v_mul_f32_e32 v21, v21, v22
	v_mul_f32_e32 v16, v16, v25
	v_mul_f32_e32 v17, v17, v23
	v_cvt_pk_bf16_f32 v20, v20, v21
	v_cvt_pk_bf16_f32 v21, v16, v17
	v_lshl_add_u64 v[16:17], s[12:13], 0, v[18:19]
	v_lshl_add_u64 v[16:17], v[16:17], 0, v[126:127]
	global_store_dwordx2 v[16:17], v[20:21], off offset:2048
	s_waitcnt vmcnt(63)
	v_mov_b64_e32 v[18:19], v[160:161]
	v_mov_b64_e32 v[20:21], v[162:163]
	v_pk_add_f32 v[10:11], v[10:11], v[18:19]
	s_waitcnt vmcnt(3)
	v_mov_b64_e32 v[18:19], v[182:183]
	v_mul_f32_e32 v10, 0xbfb8aa3b, v10
	v_mul_f32_e32 v11, 0xbfb8aa3b, v11
	v_exp_f32_e32 v10, v10
	v_exp_f32_e32 v11, v11
	v_pk_add_f32 v[12:13], v[12:13], v[20:21]
	v_add_f32_e32 v10, 1.0, v10
	v_add_f32_e32 v11, 1.0, v11
	v_rcp_f32_e32 v10, v10
	v_rcp_f32_e32 v11, v11
	v_lshlrev_b32_e32 v20, 16, v18
	v_and_b32_e32 v18, 0xffff0000, v18
	v_mul_f32_e32 v10, v10, v20
	v_mul_f32_e32 v11, v11, v18
	v_cvt_pk_bf16_f32 v10, v10, v11
	v_mul_f32_e32 v11, 0xbfb8aa3b, v12
	v_exp_f32_e32 v11, v11
	v_mul_f32_e32 v12, 0xbfb8aa3b, v13
	v_exp_f32_e32 v12, v12
	v_lshlrev_b32_e32 v21, 16, v19
	v_add_f32_e32 v11, 1.0, v11
	v_rcp_f32_e32 v11, v11
	v_add_f32_e32 v12, 1.0, v12
	v_rcp_f32_e32 v12, v12
	v_and_b32_e32 v19, 0xffff0000, v19
	v_mul_f32_e32 v11, v11, v21
	v_mul_f32_e32 v12, v12, v19
	v_cvt_pk_bf16_f32 v11, v11, v12
	global_store_dwordx2 v[16:17], v[10:11], off offset:2080
	s_waitcnt vmcnt(63)
	v_mov_b64_e32 v[10:11], v[164:165]
	v_mov_b64_e32 v[12:13], v[166:167]
	v_pk_add_f32 v[6:7], v[6:7], v[10:11]
	s_waitcnt vmcnt(3)
	v_mov_b64_e32 v[10:11], v[184:185]
	v_mul_f32_e32 v6, 0xbfb8aa3b, v6
	v_mul_f32_e32 v7, 0xbfb8aa3b, v7
	v_exp_f32_e32 v6, v6
	v_exp_f32_e32 v7, v7
	v_pk_add_f32 v[8:9], v[8:9], v[12:13]
	v_add_f32_e32 v6, 1.0, v6
	v_add_f32_e32 v7, 1.0, v7
	v_rcp_f32_e32 v6, v6
	v_rcp_f32_e32 v7, v7
	v_lshlrev_b32_e32 v12, 16, v10
	v_and_b32_e32 v10, 0xffff0000, v10
	v_mul_f32_e32 v6, v6, v12
	v_mul_f32_e32 v7, v7, v10
	v_cvt_pk_bf16_f32 v6, v6, v7
	v_mul_f32_e32 v7, 0xbfb8aa3b, v8
	v_exp_f32_e32 v7, v7
	v_mul_f32_e32 v8, 0xbfb8aa3b, v9
	v_exp_f32_e32 v8, v8
	v_lshlrev_b32_e32 v13, 16, v11
	v_add_f32_e32 v7, 1.0, v7
	v_rcp_f32_e32 v7, v7
	v_add_f32_e32 v8, 1.0, v8
	v_rcp_f32_e32 v8, v8
	v_and_b32_e32 v11, 0xffff0000, v11
	v_mul_f32_e32 v7, v7, v13
	v_mul_f32_e32 v8, v8, v11
	v_cvt_pk_bf16_f32 v7, v7, v8
	global_store_dwordx2 v[16:17], v[6:7], off offset:2304
	s_waitcnt vmcnt(63)
	v_mov_b64_e32 v[6:7], v[168:169]
	v_mov_b64_e32 v[8:9], v[170:171]
	v_pk_add_f32 v[2:3], v[2:3], v[6:7]
	s_waitcnt vmcnt(3)
	v_mov_b64_e32 v[6:7], v[186:187]
	v_mul_f32_e32 v2, 0xbfb8aa3b, v2
	v_mul_f32_e32 v3, 0xbfb8aa3b, v3
	v_exp_f32_e32 v2, v2
	v_exp_f32_e32 v3, v3
	v_pk_add_f32 v[4:5], v[4:5], v[8:9]
	v_add_f32_e32 v2, 1.0, v2
	v_add_f32_e32 v3, 1.0, v3
	v_rcp_f32_e32 v2, v2
	v_rcp_f32_e32 v3, v3
	v_lshlrev_b32_e32 v8, 16, v6
	v_and_b32_e32 v6, 0xffff0000, v6
	v_mul_f32_e32 v2, v2, v8
	v_mul_f32_e32 v3, v3, v6
	v_cvt_pk_bf16_f32 v2, v2, v3
	v_mul_f32_e32 v3, 0xbfb8aa3b, v4
	v_exp_f32_e32 v3, v3
	v_mul_f32_e32 v4, 0xbfb8aa3b, v5
	v_exp_f32_e32 v4, v4
	v_lshlrev_b32_e32 v9, 16, v7
	v_add_f32_e32 v3, 1.0, v3
	v_rcp_f32_e32 v3, v3
	v_add_f32_e32 v4, 1.0, v4
	v_rcp_f32_e32 v4, v4
	v_and_b32_e32 v7, 0xffff0000, v7
	v_mul_f32_e32 v3, v3, v9
	v_mul_f32_e32 v4, v4, v7
	v_cvt_pk_bf16_f32 v3, v3, v4
	global_store_dwordx2 v[16:17], v[2:3], off offset:2336
	s_cbranch_vccnz .LBB0_786
	s_andn2_b64 vcc, exec, s[10:11]
	s_cbranch_vccnz .LBB0_785
	s_barrier
	s_branch .LBB0_785

.LBB0_812:
	s_lshl_b32 s29, s29, 8
	s_and_b32 s29, s29, 0x100
	s_mul_hi_i32 s30, s34, 0x1100
	s_mulk_i32 s34, 0x1100
	s_add_u32 s66, s34, s66
	s_addc_u32 s67, s30, s67
	s_lshl_b32 s30, s29, 1
	s_lshl_b32 s29, s29, 2
	v_lshlrev_b32_e32 v150, 2, v138
	s_add_u32 s42, s25, s29
	v_ashrrev_i32_e32 v151, 31, v150
	s_addc_u32 s43, s27, 0
	v_lshl_add_u64 v[138:139], v[150:151], 2, s[42:43]
	global_load_dwordx4 v[156:159], v[138:139], off
	global_load_dwordx4 v[160:163], v[138:139], off offset:64
	global_load_dwordx4 v[164:167], v[138:139], off offset:512
	global_load_dwordx4 v[168:171], v[138:139], off offset:576
	s_waitcnt vmcnt(3)
	v_mov_b64_e32 v[146:147], v[156:157]
	v_mov_b64_e32 v[148:149], v[158:159]
	v_add_u32_e32 v140, s19, v140
	v_mul_lo_u32 v152, s33, v140
	v_ashrrev_i32_e32 v153, 31, v152
	v_lshlrev_b64 v[140:141], 1, v[150:151]
	v_lshl_add_u64 v[150:151], s[66:67], 0, v[152:153]
	v_lshlrev_b64 v[150:151], 12, v[150:151]
	v_lshl_add_u64 v[150:151], s[54:55], 0, v[150:151]
	s_mov_b32 s61, s31
	v_lshl_add_u64 v[150:151], v[150:151], 0, s[30:31]
	v_lshl_add_u64 v[150:151], v[150:151], 0, s[60:61]
	v_lshl_add_u64 v[150:151], v[150:151], 0, v[140:141]
	s_lshl_b32 s29, s33, 4
	s_mulk_i32 s33, 0x50
	s_andn2_b64 vcc, exec, s[64:65]
	s_mov_b64 s[64:65], -1
	v_pk_add_f32 v[126:127], v[126:127], v[146:147]
	v_pk_add_f32 v[128:129], v[128:129], v[148:149]
	v_cvt_pk_bf16_f32 v126, v126, v127
	s_nop 0
	v_cvt_pk_bf16_f32 v127, v128, v129
	global_store_dwordx2 v[150:151], v[126:127], off offset:3072
	s_waitcnt vmcnt(3)
	v_mov_b64_e32 v[126:127], v[160:161]
	v_mov_b64_e32 v[128:129], v[162:163]
	v_pk_add_f32 v[122:123], v[122:123], v[126:127]
	v_pk_add_f32 v[124:125], v[124:125], v[128:129]
	v_cvt_pk_bf16_f32 v122, v122, v123
	s_nop 0
	v_cvt_pk_bf16_f32 v123, v124, v125
	global_store_dwordx2 v[150:151], v[122:123], off offset:3104
	s_waitcnt vmcnt(3)
	v_mov_b64_e32 v[122:123], v[164:165]
	v_mov_b64_e32 v[124:125], v[166:167]
	v_pk_add_f32 v[118:119], v[118:119], v[122:123]
	v_pk_add_f32 v[120:121], v[120:121], v[124:125]
	v_cvt_pk_bf16_f32 v118, v118, v119
	s_nop 0
	v_cvt_pk_bf16_f32 v119, v120, v121
	global_store_dwordx2 v[150:151], v[118:119], off offset:3328
	s_waitcnt vmcnt(3)
	v_mov_b64_e32 v[118:119], v[168:169]
	v_mov_b64_e32 v[120:121], v[170:171]
	v_pk_add_f32 v[114:115], v[114:115], v[118:119]
	v_pk_add_f32 v[116:117], v[116:117], v[120:121]
	v_cvt_pk_bf16_f32 v114, v114, v115
	v_add_u32_e32 v118, s29, v152
	v_cvt_pk_bf16_f32 v115, v116, v117
	global_store_dwordx2 v[150:151], v[114:115], off offset:3360
	s_waitcnt vmcnt(7)
	v_mov_b64_e32 v[114:115], v[156:157]
	v_mov_b64_e32 v[116:117], v[158:159]
	v_ashrrev_i32_e32 v119, 31, v118
	v_lshl_add_u64 v[120:121], s[66:67], 0, v[118:119]
	v_lshlrev_b64 v[120:121], 12, v[120:121]
	v_lshl_add_u64 v[120:121], s[54:55], 0, v[120:121]
	v_lshl_add_u64 v[120:121], v[120:121], 0, s[30:31]
	v_lshl_add_u64 v[120:121], v[120:121], 0, s[60:61]
	v_lshl_add_u64 v[120:121], v[120:121], 0, v[140:141]
	v_pk_add_f32 v[110:111], v[110:111], v[114:115]
	v_pk_add_f32 v[112:113], v[112:113], v[116:117]
	v_cvt_pk_bf16_f32 v110, v110, v111
	s_nop 0
	v_cvt_pk_bf16_f32 v111, v112, v113
	global_store_dwordx2 v[120:121], v[110:111], off offset:3072
	s_waitcnt vmcnt(7)
	v_mov_b64_e32 v[110:111], v[160:161]
	v_mov_b64_e32 v[112:113], v[162:163]
	v_pk_add_f32 v[106:107], v[106:107], v[110:111]
	v_pk_add_f32 v[108:109], v[108:109], v[112:113]
	v_cvt_pk_bf16_f32 v106, v106, v107
	s_nop 0
	v_cvt_pk_bf16_f32 v107, v108, v109
	global_store_dwordx2 v[120:121], v[106:107], off offset:3104
	s_waitcnt vmcnt(7)
	v_mov_b64_e32 v[106:107], v[164:165]
	v_mov_b64_e32 v[108:109], v[166:167]
	v_pk_add_f32 v[102:103], v[102:103], v[106:107]
	v_pk_add_f32 v[104:105], v[104:105], v[108:109]
	v_cvt_pk_bf16_f32 v102, v102, v103
	s_nop 0
	v_cvt_pk_bf16_f32 v103, v104, v105
	global_store_dwordx2 v[120:121], v[102:103], off offset:3328
	s_waitcnt vmcnt(7)
	v_mov_b64_e32 v[102:103], v[168:169]
	v_mov_b64_e32 v[104:105], v[170:171]
	v_pk_add_f32 v[98:99], v[98:99], v[102:103]
	v_pk_add_f32 v[100:101], v[100:101], v[104:105]
	v_cvt_pk_bf16_f32 v98, v98, v99
	v_add_u32_e32 v102, s29, v118
	v_cvt_pk_bf16_f32 v99, v100, v101
	global_store_dwordx2 v[120:121], v[98:99], off offset:3360
	s_waitcnt vmcnt(11)
	v_mov_b64_e32 v[98:99], v[156:157]
	v_mov_b64_e32 v[100:101], v[158:159]
	v_ashrrev_i32_e32 v103, 31, v102
	v_lshl_add_u64 v[104:105], s[66:67], 0, v[102:103]
	v_lshlrev_b64 v[104:105], 12, v[104:105]
	v_lshl_add_u64 v[104:105], s[54:55], 0, v[104:105]
	v_lshl_add_u64 v[104:105], v[104:105], 0, s[30:31]
	v_lshl_add_u64 v[104:105], v[104:105], 0, s[60:61]
	v_lshl_add_u64 v[104:105], v[104:105], 0, v[140:141]
	v_pk_add_f32 v[94:95], v[94:95], v[98:99]
	v_pk_add_f32 v[96:97], v[96:97], v[100:101]
	v_cvt_pk_bf16_f32 v94, v94, v95
	s_nop 0
	v_cvt_pk_bf16_f32 v95, v96, v97
	global_store_dwordx2 v[104:105], v[94:95], off offset:3072
	s_waitcnt vmcnt(11)
	v_mov_b64_e32 v[94:95], v[160:161]
	v_mov_b64_e32 v[96:97], v[162:163]
	v_pk_add_f32 v[90:91], v[90:91], v[94:95]
	v_pk_add_f32 v[92:93], v[92:93], v[96:97]
	v_cvt_pk_bf16_f32 v90, v90, v91
	s_nop 0
	v_cvt_pk_bf16_f32 v91, v92, v93
	global_store_dwordx2 v[104:105], v[90:91], off offset:3104
	s_waitcnt vmcnt(11)
	v_mov_b64_e32 v[90:91], v[164:165]
	v_mov_b64_e32 v[92:93], v[166:167]
	v_pk_add_f32 v[86:87], v[86:87], v[90:91]
	v_pk_add_f32 v[88:89], v[88:89], v[92:93]
	v_cvt_pk_bf16_f32 v86, v86, v87
	s_nop 0
	v_cvt_pk_bf16_f32 v87, v88, v89
	global_store_dwordx2 v[104:105], v[86:87], off offset:3328
	s_waitcnt vmcnt(11)
	v_mov_b64_e32 v[86:87], v[168:169]
	v_mov_b64_e32 v[88:89], v[170:171]
	v_pk_add_f32 v[82:83], v[82:83], v[86:87]
	v_pk_add_f32 v[84:85], v[84:85], v[88:89]
	v_cvt_pk_bf16_f32 v82, v82, v83
	v_add_u32_e32 v86, s29, v102
	v_cvt_pk_bf16_f32 v83, v84, v85
	global_store_dwordx2 v[104:105], v[82:83], off offset:3360
	s_waitcnt vmcnt(15)
	v_mov_b64_e32 v[82:83], v[156:157]
	v_mov_b64_e32 v[84:85], v[158:159]
	v_ashrrev_i32_e32 v87, 31, v86
	v_lshl_add_u64 v[88:89], s[66:67], 0, v[86:87]
	v_lshlrev_b64 v[88:89], 12, v[88:89]
	v_lshl_add_u64 v[88:89], s[54:55], 0, v[88:89]
	v_lshl_add_u64 v[88:89], v[88:89], 0, s[30:31]
	v_lshl_add_u64 v[88:89], v[88:89], 0, s[60:61]
	v_lshl_add_u64 v[88:89], v[88:89], 0, v[140:141]
	v_pk_add_f32 v[78:79], v[78:79], v[82:83]
	v_pk_add_f32 v[80:81], v[80:81], v[84:85]
	v_cvt_pk_bf16_f32 v78, v78, v79
	s_nop 0
	v_cvt_pk_bf16_f32 v79, v80, v81
	global_store_dwordx2 v[88:89], v[78:79], off offset:3072
	s_waitcnt vmcnt(15)
	v_mov_b64_e32 v[78:79], v[160:161]
	v_mov_b64_e32 v[80:81], v[162:163]
	v_pk_add_f32 v[74:75], v[74:75], v[78:79]
	v_pk_add_f32 v[76:77], v[76:77], v[80:81]
	v_cvt_pk_bf16_f32 v74, v74, v75
	s_nop 0
	v_cvt_pk_bf16_f32 v75, v76, v77
	global_store_dwordx2 v[88:89], v[74:75], off offset:3104
	s_waitcnt vmcnt(15)
	v_mov_b64_e32 v[74:75], v[164:165]
	v_mov_b64_e32 v[76:77], v[166:167]
	v_pk_add_f32 v[70:71], v[70:71], v[74:75]
	v_pk_add_f32 v[72:73], v[72:73], v[76:77]
	v_cvt_pk_bf16_f32 v70, v70, v71
	s_nop 0
	v_cvt_pk_bf16_f32 v71, v72, v73
	global_store_dwordx2 v[88:89], v[70:71], off offset:3328
	s_waitcnt vmcnt(15)
	v_mov_b64_e32 v[70:71], v[168:169]
	v_mov_b64_e32 v[72:73], v[170:171]
	v_pk_add_f32 v[66:67], v[66:67], v[70:71]
	v_pk_add_f32 v[68:69], v[68:69], v[72:73]
	v_cvt_pk_bf16_f32 v66, v66, v67
	v_add_u32_e32 v70, s33, v86
	v_cvt_pk_bf16_f32 v67, v68, v69
	global_store_dwordx2 v[88:89], v[66:67], off offset:3360
	s_waitcnt vmcnt(19)
	v_mov_b64_e32 v[66:67], v[156:157]
	v_mov_b64_e32 v[68:69], v[158:159]
	v_ashrrev_i32_e32 v71, 31, v70
	v_lshl_add_u64 v[72:73], s[66:67], 0, v[70:71]
	v_lshlrev_b64 v[72:73], 12, v[72:73]
	v_lshl_add_u64 v[72:73], s[54:55], 0, v[72:73]
	v_lshl_add_u64 v[72:73], v[72:73], 0, s[30:31]
	v_lshl_add_u64 v[72:73], v[72:73], 0, s[60:61]
	v_lshl_add_u64 v[72:73], v[72:73], 0, v[140:141]
	v_pk_add_f32 v[62:63], v[62:63], v[66:67]
	v_pk_add_f32 v[64:65], v[64:65], v[68:69]
	v_cvt_pk_bf16_f32 v62, v62, v63
	s_nop 0
	v_cvt_pk_bf16_f32 v63, v64, v65
	global_store_dwordx2 v[72:73], v[62:63], off offset:3072
	s_waitcnt vmcnt(19)
	v_mov_b64_e32 v[62:63], v[160:161]
	v_mov_b64_e32 v[64:65], v[162:163]
	v_pk_add_f32 v[58:59], v[58:59], v[62:63]
	v_pk_add_f32 v[60:61], v[60:61], v[64:65]
	v_cvt_pk_bf16_f32 v58, v58, v59
	s_nop 0
	v_cvt_pk_bf16_f32 v59, v60, v61
	global_store_dwordx2 v[72:73], v[58:59], off offset:3104
	s_waitcnt vmcnt(19)
	v_mov_b64_e32 v[58:59], v[164:165]
	v_mov_b64_e32 v[60:61], v[166:167]
	v_pk_add_f32 v[54:55], v[54:55], v[58:59]
	v_pk_add_f32 v[56:57], v[56:57], v[60:61]
	v_cvt_pk_bf16_f32 v54, v54, v55
	s_nop 0
	v_cvt_pk_bf16_f32 v55, v56, v57
	global_store_dwordx2 v[72:73], v[54:55], off offset:3328
	s_waitcnt vmcnt(19)
	v_mov_b64_e32 v[54:55], v[168:169]
	v_mov_b64_e32 v[56:57], v[170:171]
	v_pk_add_f32 v[50:51], v[50:51], v[54:55]
	v_pk_add_f32 v[52:53], v[52:53], v[56:57]
	v_cvt_pk_bf16_f32 v50, v50, v51
	v_add_u32_e32 v54, s29, v70
	v_cvt_pk_bf16_f32 v51, v52, v53
	global_store_dwordx2 v[72:73], v[50:51], off offset:3360
	s_waitcnt vmcnt(23)
	v_mov_b64_e32 v[50:51], v[156:157]
	v_mov_b64_e32 v[52:53], v[158:159]
	v_ashrrev_i32_e32 v55, 31, v54
	v_lshl_add_u64 v[56:57], s[66:67], 0, v[54:55]
	v_lshlrev_b64 v[56:57], 12, v[56:57]
	v_lshl_add_u64 v[56:57], s[54:55], 0, v[56:57]
	v_lshl_add_u64 v[56:57], v[56:57], 0, s[30:31]
	v_lshl_add_u64 v[56:57], v[56:57], 0, s[60:61]
	v_lshl_add_u64 v[56:57], v[56:57], 0, v[140:141]
	v_pk_add_f32 v[46:47], v[46:47], v[50:51]
	v_pk_add_f32 v[48:49], v[48:49], v[52:53]
	v_cvt_pk_bf16_f32 v46, v46, v47
	s_nop 0
	v_cvt_pk_bf16_f32 v47, v48, v49
	global_store_dwordx2 v[56:57], v[46:47], off offset:3072
	s_waitcnt vmcnt(23)
; #define PG8_BAR __builtin_amdgcn_s_barrier()
;     ...
;     if (!has_next) break;
; #pragma unroll
;     for (int a = 0; a < 2; ++a)
; #pragma unroll
;       for (int b = 0; b < 2; ++b)
; #pragma unroll
;         for (int m = 0; m < 4; ++m)
; #pragma unroll
;           for (int n = 0; n < 2; ++n) acc[a][b][m][n] = (f32x4){0.f, 0.f, 0.f, 0.f};
;     cur = nxt; cA = nA; cB = nB; ++ui;
;     if (wr == 1) PG8_BAR;
	v_mov_b64_e32 v[46:47], v[160:161]
	v_mov_b64_e32 v[48:49], v[162:163]
	v_pk_add_f32 v[42:43], v[42:43], v[46:47]
	v_pk_add_f32 v[44:45], v[44:45], v[48:49]
	v_cvt_pk_bf16_f32 v42, v42, v43
	s_nop 0
	v_cvt_pk_bf16_f32 v43, v44, v45
	global_store_dwordx2 v[56:57], v[42:43], off offset:3104
	s_waitcnt vmcnt(23)
	v_mov_b64_e32 v[42:43], v[164:165]
	v_mov_b64_e32 v[44:45], v[166:167]
	v_pk_add_f32 v[38:39], v[38:39], v[42:43]
	v_pk_add_f32 v[40:41], v[40:41], v[44:45]
	v_cvt_pk_bf16_f32 v38, v38, v39
	s_nop 0
	v_cvt_pk_bf16_f32 v39, v40, v41
	global_store_dwordx2 v[56:57], v[38:39], off offset:3328
	s_waitcnt vmcnt(23)
	v_mov_b64_e32 v[38:39], v[168:169]
	v_mov_b64_e32 v[40:41], v[170:171]
	v_pk_add_f32 v[34:35], v[34:35], v[38:39]
	v_pk_add_f32 v[36:37], v[36:37], v[40:41]
	v_cvt_pk_bf16_f32 v34, v34, v35
	v_add_u32_e32 v38, s29, v54
	v_cvt_pk_bf16_f32 v35, v36, v37
	global_store_dwordx2 v[56:57], v[34:35], off offset:3360
	s_waitcnt vmcnt(27)
	v_mov_b64_e32 v[34:35], v[156:157]
	v_mov_b64_e32 v[36:37], v[158:159]
	v_ashrrev_i32_e32 v39, 31, v38
	v_lshl_add_u64 v[40:41], s[66:67], 0, v[38:39]
	v_lshlrev_b64 v[40:41], 12, v[40:41]
	v_lshl_add_u64 v[40:41], s[54:55], 0, v[40:41]
	v_lshl_add_u64 v[40:41], v[40:41], 0, s[30:31]
	v_lshl_add_u64 v[40:41], v[40:41], 0, s[60:61]
	v_lshl_add_u64 v[40:41], v[40:41], 0, v[140:141]
	v_pk_add_f32 v[30:31], v[30:31], v[34:35]
	v_pk_add_f32 v[32:33], v[32:33], v[36:37]
	v_cvt_pk_bf16_f32 v30, v30, v31
	s_nop 0
	v_cvt_pk_bf16_f32 v31, v32, v33
	global_store_dwordx2 v[40:41], v[30:31], off offset:3072
	s_waitcnt vmcnt(27)
	v_mov_b64_e32 v[30:31], v[160:161]
	v_mov_b64_e32 v[32:33], v[162:163]
	v_pk_add_f32 v[26:27], v[26:27], v[30:31]
	v_pk_add_f32 v[28:29], v[28:29], v[32:33]
	v_cvt_pk_bf16_f32 v26, v26, v27
	s_nop 0
	v_cvt_pk_bf16_f32 v27, v28, v29
	global_store_dwordx2 v[40:41], v[26:27], off offset:3104
	s_waitcnt vmcnt(27)
	v_mov_b64_e32 v[26:27], v[164:165]
	v_mov_b64_e32 v[28:29], v[166:167]
	v_pk_add_f32 v[22:23], v[22:23], v[26:27]
	v_pk_add_f32 v[24:25], v[24:25], v[28:29]
	v_cvt_pk_bf16_f32 v22, v22, v23
	s_nop 0
	v_cvt_pk_bf16_f32 v23, v24, v25
	global_store_dwordx2 v[40:41], v[22:23], off offset:3328
	s_waitcnt vmcnt(27)
	v_mov_b64_e32 v[22:23], v[168:169]
	v_mov_b64_e32 v[24:25], v[170:171]
	v_pk_add_f32 v[18:19], v[18:19], v[22:23]
	v_pk_add_f32 v[20:21], v[20:21], v[24:25]
	v_cvt_pk_bf16_f32 v18, v18, v19
	v_add_u32_e32 v22, s29, v38
	v_cvt_pk_bf16_f32 v19, v20, v21
	global_store_dwordx2 v[40:41], v[18:19], off offset:3360
	s_waitcnt vmcnt(31)
	v_mov_b64_e32 v[18:19], v[156:157]
	v_mov_b64_e32 v[20:21], v[158:159]
	v_ashrrev_i32_e32 v23, 31, v22
	v_lshl_add_u64 v[22:23], s[66:67], 0, v[22:23]
	v_lshlrev_b64 v[22:23], 12, v[22:23]
	v_lshl_add_u64 v[22:23], s[54:55], 0, v[22:23]
	v_lshl_add_u64 v[22:23], v[22:23], 0, s[30:31]
	v_lshl_add_u64 v[22:23], v[22:23], 0, s[60:61]
	v_lshl_add_u64 v[22:23], v[22:23], 0, v[140:141]
	v_pk_add_f32 v[14:15], v[14:15], v[18:19]
	v_pk_add_f32 v[16:17], v[16:17], v[20:21]
	v_cvt_pk_bf16_f32 v14, v14, v15
	s_nop 0
	v_cvt_pk_bf16_f32 v15, v16, v17
	global_store_dwordx2 v[22:23], v[14:15], off offset:3072
	s_waitcnt vmcnt(31)
	v_mov_b64_e32 v[14:15], v[160:161]
	v_mov_b64_e32 v[16:17], v[162:163]
	v_pk_add_f32 v[10:11], v[10:11], v[14:15]
	v_pk_add_f32 v[12:13], v[12:13], v[16:17]
	v_cvt_pk_bf16_f32 v10, v10, v11
	s_nop 0
	v_cvt_pk_bf16_f32 v11, v12, v13
	global_store_dwordx2 v[22:23], v[10:11], off offset:3104
	s_waitcnt vmcnt(31)
	v_mov_b64_e32 v[10:11], v[164:165]
	v_mov_b64_e32 v[12:13], v[166:167]
	v_pk_add_f32 v[6:7], v[6:7], v[10:11]
	v_pk_add_f32 v[8:9], v[8:9], v[12:13]
	v_cvt_pk_bf16_f32 v6, v6, v7
	s_nop 0
	v_cvt_pk_bf16_f32 v7, v8, v9
	global_store_dwordx2 v[22:23], v[6:7], off offset:3328
	s_waitcnt vmcnt(31)
	v_mov_b64_e32 v[6:7], v[168:169]
	v_mov_b64_e32 v[8:9], v[170:171]
	v_pk_add_f32 v[2:3], v[2:3], v[6:7]
	v_pk_add_f32 v[4:5], v[4:5], v[8:9]
	v_cvt_pk_bf16_f32 v2, v2, v3
	s_nop 0
	v_cvt_pk_bf16_f32 v3, v4, v5
	global_store_dwordx2 v[22:23], v[2:3], off offset:3360
	s_cbranch_vccnz .LBB0_803
	s_andn2_b64 vcc, exec, s[14:15]
	s_cbranch_vccnz .LBB0_802
	s_barrier
	s_branch .LBB0_802
